# v42 + P4/P9: row rstd kept in v240-247 and rms prelude skipped when the unit's row block equals the previous unit's
# speedup vs baseline: 1.0111x; 1.0111x over previous
.LBB0_474:
	s_mov_b32 s62, -1
	s_or_b64 exec, exec, s[6:7]
	s_cmpk_lt_i32 s2, 0xb00
	s_cselect_b64 s[4:5], -1, 0
	v_writelane_b32 v254, s4, 6
	s_waitcnt lgkmcnt(0)
	v_mov_b32_e32 v0, v202
	v_mov_b32_e32 v9, v202
	v_writelane_b32 v254, s5, 7
	s_mov_b64 s[4:5], s[0:1]
	s_barrier
	s_cmpk_gt_i32 s2, 0xaff
	s_nop 0
	v_readfirstlane_b32 s13, v9
	s_cbranch_scc1 .LBB0_490
	v_lshlrev_b32_e32 v0, 4, v9
	v_add_u32_e32 v1, 0x2000, v0
	v_ashrrev_i32_e32 v2, 31, v1
	v_lshrrev_b32_e32 v2, 22, v2
	v_add_u32_e32 v2, v1, v2
	v_ashrrev_i32_e32 v8, 10, v2
	v_mul_i32_i24_e32 v2, 0x400, v8
	v_sub_u32_e32 v1, v1, v2
	v_lshrrev_b32_e32 v2, 4, v1
	v_bitop3_b32 v1, v2, v1, 32 bitop3:0x6c
	v_ashrrev_i32_e32 v2, 31, v1
	v_lshrrev_b32_e32 v2, 26, v2
	v_add_u32_e32 v2, v1, v2
	v_lshlrev_b32_e32 v3, 3, v8
	v_ashrrev_i32_e32 v10, 6, v2
	v_and_b32_e32 v3, -16, v3
	v_add_u32_e32 v3, v10, v3
	s_load_dwordx2 s[6:7], s[4:5], 0xa0
	v_and_b32_e32 v4, 3, v10
	s_mov_b32 s4, 0x1fffe0
	v_lshrrev_b32_e32 v5, 2, v3
	v_lshlrev_b32_e32 v6, 1, v3
	v_and_b32_e32 v2, 0xc0, v2
	v_and_or_b32 v4, v3, s4, v4
	v_and_b32_e32 v5, 4, v5
	v_and_b32_e32 v6, 24, v6
	v_sub_u32_e32 v1, v1, v2
	v_mov_b32_e32 v2, 1
	v_or3_b32 v4, v4, v5, v6
	v_lshlrev_b32_e32 v5, 5, v8
	v_ashrrev_i16_sdwa v1, v2, sext(v1) dst_sel:DWORD dst_unused:UNUSED_PAD src0_sel:DWORD src1_sel:BYTE_0
	v_and_b32_e32 v5, 32, v5
	v_bfe_i32 v11, v1, 0, 16
	v_add_lshl_u32 v1, v5, v11, 1
	v_lshl_add_u32 v128, v4, 11, v1
	v_lshl_add_u32 v130, v3, 11, v1
	v_bfe_i32 v1, v9, 27, 1
	v_lshrrev_b32_e32 v1, 22, v1
	v_add_u32_e32 v1, v0, v1
	v_and_b32_e32 v1, 0xfffffc00, v1
	v_sub_u32_e32 v0, v0, v1
	v_lshrrev_b32_e32 v1, 4, v0
	v_ashrrev_i32_e32 v3, 31, v9
	v_bitop3_b32 v0, v1, v0, 32 bitop3:0x6c
	v_lshrrev_b32_e32 v3, 26, v3
	v_ashrrev_i32_e32 v1, 31, v0
	v_add_u32_e32 v3, v9, v3
	v_lshrrev_b32_e32 v1, 26, v1
	v_ashrrev_i32_e32 v13, 6, v3
	s_waitcnt lgkmcnt(0)
	s_add_u32 s14, s6, 0x4800000
	v_add_u32_e32 v1, v0, v1
	v_lshlrev_b32_e32 v3, 3, v13
	s_addc_u32 s15, s7, 0
	v_ashrrev_i32_e32 v12, 6, v1
	v_and_b32_e32 v3, -16, v3
	s_add_u32 s20, s6, 0x1800000
	v_add_u32_e32 v3, v12, v3
	v_and_b32_e32 v4, 3, v12
	s_addc_u32 s22, s7, 0
	v_and_or_b32 v4, v3, s4, v4
	s_lshr_b32 s4, s21, 29
	s_add_i32 s4, s2, s4
	s_ashr_i32 s28, s13, 6
	s_ashr_i32 s5, s4, 3
	s_and_b32 s4, s4, -8
	s_ashr_i32 s30, s13, 8
	s_lshl_b32 s23, s28, 10
	s_sub_i32 s4, s2, s4
	s_cmp_lt_i32 s4, 0
	s_movk_i32 s25, 0x161
	s_cselect_b32 s8, s25, 0x160
	s_mul_i32 s4, s4, s8
	s_add_i32 s4, s4, s5
	s_mul_hi_i32 s5, s4, 0x2e8ba2e9
	s_lshr_b32 s8, s5, 31
	s_ashr_i32 s5, s5, 5
	s_add_i32 s5, s5, s8
	s_lshl_b32 s8, s5, 3
	s_mulk_i32 s5, 0xb0
	s_sub_i32 s4, s4, s5
	s_sext_i32_i16 s5, s4
	s_bfe_u32 s5, s5, 0x3001c
	s_add_i32 s5, s4, s5
	s_sext_i32_i16 s9, s5
	s_and_b32 s5, s5, 0xfff8
	s_sub_i32 s4, s4, s5
	s_sext_i32_i16 s4, s4
	v_lshrrev_b32_e32 v5, 2, v3
	v_lshlrev_b32_e32 v6, 1, v3
	v_and_b32_e32 v1, 0xc0, v1
	s_lshr_b32 s12, s9, 3
	s_add_i32 s8, s8, s4
	v_and_b32_e32 v5, 4, v5
	v_and_b32_e32 v6, 24, v6
	v_sub_u32_e32 v0, v0, v1
	s_ashr_i32 s9, s8, 31
	s_bfe_i64 s[4:5], s[12:13], 0x100000
	v_or3_b32 v4, v4, v5, v6
	v_lshlrev_b32_e32 v5, 5, v13
	v_ashrrev_i16_sdwa v0, v2, sext(v0) dst_sel:DWORD dst_unused:UNUSED_PAD src0_sel:DWORD src1_sel:BYTE_0
	s_lshl_b64 s[10:11], s[8:9], 19
	s_lshl_b64 s[4:5], s[4:5], 19
	v_and_b32_e32 v5, 32, v5
	v_bfe_i32 v14, v0, 0, 16
	s_add_u32 s4, s20, s4
	v_add_lshl_u32 v0, v5, v14, 1
	s_addc_u32 s5, s22, s5
	s_add_i32 s42, s23, 0
	v_lshl_add_u32 v132, v4, 11, v0
	s_add_i32 m0, s42, 0x10000
	v_lshl_add_u32 v134, v3, 11, v0
	global_load_lds_dwordx4 v132, s[4:5]
	s_add_i32 m0, s42, 0x12000
	s_add_u32 s16, s4, 0x40000
	global_load_lds_dwordx4 v128, s[4:5]
	s_addc_u32 s17, s5, 0
	s_add_i32 m0, s42, 0x14000
	v_mov_b32_e32 v133, 0
	global_load_lds_dwordx4 v132, s[16:17]
	s_add_i32 m0, s42, 0x16000
	s_add_u32 s10, s14, s10
	s_addc_u32 s11, s15, s11
	s_add_i32 s43, s42, 0x2000
	global_load_lds_dwordx4 v128, s[16:17]
	s_mov_b32 m0, s42
	s_add_u32 s16, s10, 0x40000
	global_load_lds_dwordx4 v134, s[10:11]
	s_mov_b32 m0, s43
	s_addc_u32 s17, s11, 0
	s_add_i32 s44, s42, 0x4000
	global_load_lds_dwordx4 v130, s[10:11]
	s_mov_b32 m0, s44
	s_add_i32 s45, s42, 0x6000
	global_load_lds_dwordx4 v134, s[16:17]
	s_mov_b32 m0, s45
	v_mov_b32_e32 v129, v133
	global_load_lds_dwordx4 v130, s[16:17]
	v_mov_b32_e32 v135, v133
	v_mov_b32_e32 v131, v133
	s_cmp_eq_u32 s30, 1
	s_mov_b32 s46, 0
	v_lshl_add_u64 v[6:7], s[4:5], 0, v[132:133]
	v_lshl_add_u64 v[4:5], s[4:5], 0, v[128:129]
	v_lshl_add_u64 v[0:1], s[10:11], 0, v[134:135]
	s_cselect_b64 s[16:17], -1, 0
	s_cmp_lg_u32 s30, 1
	v_lshl_add_u64 v[2:3], s[10:11], 0, v[130:131]
	s_cbranch_scc1 .LBB0_477
	s_barrier

.LBB0_486:
	v_lshl_add_u32 v162, s8, 8, v159
	s_cmp_eq_u32 s8, s62
	s_cbranch_scc1 .Lrstd_reuse_p4
	s_mov_b64 s[60:61], 0x2000
	v_lshlrev_b32_e32 v204, 6, v162
	v_mov_b32_e32 v205, 0
	v_mbcnt_lo_u32_b32 v248, -1, 0
	v_mbcnt_hi_u32_b32 v248, -1, v248
	v_xor_b32_e32 v248, 16, v248
	v_lshl_add_u64 v[204:205], v[136:137], 0, v[204:205]
	v_lshlrev_b32_e32 v248, 2, v248
	v_lshl_add_u64 v[206:207], v[204:205], 0, s[60:61]
	global_load_dwordx4 v[208:211], v[204:205], off
	global_load_dwordx4 v[212:215], v[204:205], off offset:1024
	global_load_dwordx4 v[216:219], v[204:205], off offset:2048
	global_load_dwordx4 v[220:223], v[204:205], off offset:3072
	global_load_dwordx4 v[224:227], v[206:207], off
	global_load_dwordx4 v[228:231], v[206:207], off offset:1024
	global_load_dwordx4 v[232:235], v[206:207], off offset:2048
	global_load_dwordx4 v[236:239], v[206:207], off offset:3072
	s_waitcnt vmcnt(0)
	v_add_f32_e32 v208, v208, v209
	v_add_f32_e32 v210, v210, v211
	v_add_f32_e32 v212, v212, v213
	v_add_f32_e32 v214, v214, v215
	v_add_f32_e32 v216, v216, v217
	v_add_f32_e32 v218, v218, v219
	v_add_f32_e32 v220, v220, v221
	v_add_f32_e32 v222, v222, v223
	v_add_f32_e32 v224, v224, v225
	v_add_f32_e32 v226, v226, v227
	v_add_f32_e32 v228, v228, v229
	v_add_f32_e32 v230, v230, v231
	v_add_f32_e32 v232, v232, v233
	v_add_f32_e32 v234, v234, v235
	v_add_f32_e32 v236, v236, v237
	v_add_f32_e32 v238, v238, v239
	v_add_f32_e32 v208, v208, v210
	v_add_f32_e32 v212, v212, v214
	v_add_f32_e32 v216, v216, v218
	v_add_f32_e32 v220, v220, v222
	v_add_f32_e32 v224, v224, v226
	v_add_f32_e32 v228, v228, v230
	v_add_f32_e32 v232, v232, v234
	v_add_f32_e32 v236, v236, v238
	ds_bpermute_b32 v209, v248, v208
	ds_bpermute_b32 v213, v248, v212
	ds_bpermute_b32 v217, v248, v216
	ds_bpermute_b32 v221, v248, v220
	ds_bpermute_b32 v225, v248, v224
	ds_bpermute_b32 v229, v248, v228
	ds_bpermute_b32 v233, v248, v232
	ds_bpermute_b32 v237, v248, v236
	s_waitcnt lgkmcnt(0)
	v_add_f32_e32 v208, v208, v209
	v_add_f32_e32 v212, v212, v213
	v_add_f32_e32 v216, v216, v217
	v_add_f32_e32 v220, v220, v221
	v_add_f32_e32 v224, v224, v225
	v_add_f32_e32 v228, v228, v229
	v_add_f32_e32 v232, v232, v233
	v_add_f32_e32 v236, v236, v237
	v_mov_b32_e32 v209, v208
	v_mov_b32_e32 v213, v212
	v_mov_b32_e32 v217, v216
	v_mov_b32_e32 v221, v220
	v_mov_b32_e32 v225, v224
	v_mov_b32_e32 v229, v228
	v_mov_b32_e32 v233, v232
	v_mov_b32_e32 v237, v236
	s_nop 1
	v_permlane32_swap_b32_e32 v208, v209
	v_permlane32_swap_b32_e32 v212, v213
	v_permlane32_swap_b32_e32 v216, v217
	v_permlane32_swap_b32_e32 v220, v221
	v_permlane32_swap_b32_e32 v224, v225
	v_permlane32_swap_b32_e32 v228, v229
	v_permlane32_swap_b32_e32 v232, v233
	v_permlane32_swap_b32_e32 v236, v237
	v_add_f32_e32 v208, v208, v209
	v_add_f32_e32 v212, v212, v213
	v_add_f32_e32 v216, v216, v217
	v_add_f32_e32 v220, v220, v221
	v_add_f32_e32 v224, v224, v225
	v_add_f32_e32 v228, v228, v229
	v_add_f32_e32 v232, v232, v233
	v_add_f32_e32 v236, v236, v237
	v_fmamk_f32 v208, v208, 0x3a800000, v177
	v_fmamk_f32 v212, v212, 0x3a800000, v177
	v_fmamk_f32 v216, v216, 0x3a800000, v177
	v_fmamk_f32 v220, v220, 0x3a800000, v177
	v_fmamk_f32 v224, v224, 0x3a800000, v177
	v_fmamk_f32 v228, v228, 0x3a800000, v177
	v_fmamk_f32 v232, v232, 0x3a800000, v177
	v_fmamk_f32 v236, v236, 0x3a800000, v177
	v_rsq_f32_e32 v176, v208
	v_rsq_f32_e32 v174, v212
	v_rsq_f32_e32 v172, v216
	v_rsq_f32_e32 v170, v220
	v_rsq_f32_e32 v168, v224
	v_rsq_f32_e32 v166, v228
	v_rsq_f32_e32 v164, v232
	v_rsq_f32_e32 v158, v236
	s_nop 0
	v_mov_b32_e32 v240, v176
	v_mov_b32_e32 v241, v174
	v_mov_b32_e32 v242, v172
	v_mov_b32_e32 v243, v170
	v_mov_b32_e32 v244, v168
	v_mov_b32_e32 v245, v166
	v_mov_b32_e32 v246, v164
	v_mov_b32_e32 v247, v158
	s_mov_b32 s62, s8
	s_branch .Lrstd_done_p4
.Lrstd_reuse_p4:
	v_mov_b32_e32 v176, v240
	v_mov_b32_e32 v174, v241
	v_mov_b32_e32 v172, v242
	v_mov_b32_e32 v170, v243
	v_mov_b32_e32 v168, v244
	v_mov_b32_e32 v166, v245
	v_mov_b32_e32 v164, v246
	v_mov_b32_e32 v158, v247
.Lrstd_done_p4:
	v_or_b32_e32 v160, 16, v162
	v_or_b32_e32 v156, 32, v162
	v_or_b32_e32 v154, 48, v162
	v_add_u32_e32 v148, 0x80, v162
	s_nop 0
	s_nop 0
	v_add_u32_e32 v152, 0x90, v162
	v_add_u32_e32 v150, 0xa0, v162
	s_nop 0
	s_nop 1
	v_add_u32_e32 v146, 0xb0, v162
	s_waitcnt lgkmcnt(0)
	s_waitcnt lgkmcnt(0)
	s_waitcnt vmcnt(1)
	s_waitcnt lgkmcnt(0)
	s_waitcnt lgkmcnt(0)
	s_waitcnt vmcnt(0)
	v_mov_b32_e32 v180, v120
	s_waitcnt lgkmcnt(0)
	s_waitcnt lgkmcnt(0)
	v_mov_b32_e32 v181, v124
	v_pk_mul_f32 v[180:181], v[180:181], v[176:177] op_sel_hi:[1,0]
	v_mov_b32_e32 v124, v121
	v_mul_f32_e32 v120, 0xbfb8aa3b, v181
	v_exp_f32_e32 v147, v120
	v_pk_mul_f32 v[120:121], v[124:125], v[176:177] op_sel_hi:[1,0]
	s_andn2_b64 vcc, exec, s[6:7]
	v_mul_f32_e32 v124, 0xbfb8aa3b, v121
	v_exp_f32_e32 v125, v124
	v_add_f32_e32 v147, 1.0, v147
	v_rcp_f32_e32 v147, v147
	v_lshl_or_b32 v124, s33, 7, v167
	v_add_f32_e32 v125, 1.0, v125
	v_rcp_f32_e32 v149, v125
	v_mul_f32_e32 v147, v181, v147
	v_mul_f32_e32 v147, v180, v147
	v_mov_b32_e32 v180, v122
	v_mov_b32_e32 v181, v126
	v_pk_mul_f32 v[180:181], v[180:181], v[176:177] op_sel_hi:[1,0]
	v_mov_b32_e32 v126, v123
	v_mul_f32_e32 v122, 0xbfb8aa3b, v181
	v_mul_f32_e32 v121, v121, v149
	v_exp_f32_e32 v149, v122
	v_pk_mul_f32 v[122:123], v[126:127], v[176:177] op_sel_hi:[1,0]
	v_mul_f32_e32 v127, v120, v121
	v_mul_f32_e32 v126, 0xbfb8aa3b, v123
	v_exp_f32_e32 v126, v126
	v_add_f32_e32 v120, 1.0, v149
	v_rcp_f32_e32 v149, v120
	v_mov_b32_e32 v121, v116
	v_add_f32_e32 v120, 1.0, v126
	v_rcp_f32_e32 v126, v120
	v_mov_b32_e32 v120, v112
	v_pk_mul_f32 v[120:121], v[120:121], v[176:177] op_sel_hi:[1,0]
	v_mul_f32_e32 v116, v181, v149
	v_mul_f32_e32 v112, 0xbfb8aa3b, v121
	v_exp_f32_e32 v112, v112
	v_mul_f32_e32 v149, v180, v116
	v_mov_b32_e32 v116, v113
	v_mul_f32_e32 v123, v123, v126
	v_add_f32_e32 v112, 1.0, v112
	v_rcp_f32_e32 v126, v112
	v_pk_mul_f32 v[112:113], v[116:117], v[176:177] op_sel_hi:[1,0]
	v_mul_f32_e32 v122, v122, v123
	v_mul_f32_e32 v116, 0xbfb8aa3b, v113
	v_exp_f32_e32 v116, v116
	v_mul_f32_e32 v117, v121, v126
	v_mul_f32_e32 v120, v120, v117
	v_mov_b32_e32 v117, v118
	v_add_f32_e32 v116, 1.0, v116
	v_rcp_f32_e32 v121, v116
	v_mov_b32_e32 v116, v114
	v_pk_mul_f32 v[116:117], v[116:117], v[176:177] op_sel_hi:[1,0]
	v_mov_b32_e32 v118, v115
	v_mul_f32_e32 v114, 0xbfb8aa3b, v117
	v_exp_f32_e32 v123, v114
	v_pk_mul_f32 v[114:115], v[118:119], v[176:177] op_sel_hi:[1,0]
	v_mul_f32_e32 v113, v113, v121
	v_mul_f32_e32 v118, 0xbfb8aa3b, v115
	v_exp_f32_e32 v118, v118
	v_add_f32_e32 v119, 1.0, v123
	v_rcp_f32_e32 v119, v119
	v_mul_f32_e32 v112, v112, v113
	v_add_f32_e32 v118, 1.0, v118
	v_rcp_f32_e32 v118, v118
	v_mul_f32_e32 v113, v117, v119
	v_mul_f32_e32 v113, v116, v113
	v_cvt_pk_bf16_f32 v116, v147, v127
	v_cvt_pk_bf16_f32 v117, v149, v122
	v_mov_b32_e32 v122, v104
	v_mov_b32_e32 v123, v108
	v_mul_f32_e32 v115, v115, v118
	v_pk_mul_f32 v[122:123], v[122:123], v[174:175] op_sel_hi:[1,0]
	v_ashrrev_i32_e32 v125, 31, v124
	v_mul_f32_e32 v114, v114, v115
	v_mul_f32_e32 v104, 0xbfb8aa3b, v123
	v_cvt_pk_bf16_f32 v118, v120, v112
	v_cvt_pk_bf16_f32 v119, v113, v114
	v_lshlrev_b64 v[114:115], 1, v[124:125]
	v_exp_f32_e32 v124, v104
	v_mov_b32_e32 v108, v105
	v_mov_b64_e32 v[112:113], s[26:27]
	v_pk_mul_f32 v[104:105], v[108:109], v[174:175] op_sel_hi:[1,0]
	v_mad_i64_i32 v[120:121], s[4:5], v162, s52, v[112:113]
	v_mul_f32_e32 v108, 0xbfb8aa3b, v105
	v_exp_f32_e32 v125, v108
	v_lshl_add_u64 v[108:109], v[120:121], 0, v[114:115]
	v_add_f32_e32 v120, 1.0, v124
	v_rcp_f32_e32 v120, v120
	global_store_dwordx4 v[108:109], v[116:119], off
	v_mov_b32_e32 v109, v110
	v_add_f32_e32 v121, 1.0, v125
	v_mul_f32_e32 v108, v123, v120
	v_mul_f32_e32 v116, v122, v108
	v_mov_b32_e32 v108, v106
	v_pk_mul_f32 v[108:109], v[108:109], v[174:175] op_sel_hi:[1,0]
	v_mov_b32_e32 v110, v107
	v_mul_f32_e32 v106, 0xbfb8aa3b, v109
	v_rcp_f32_e32 v121, v121
	v_exp_f32_e32 v117, v106
	v_pk_mul_f32 v[106:107], v[110:111], v[174:175] op_sel_hi:[1,0]
	v_mul_f32_e32 v105, v105, v121
	v_mul_f32_e32 v110, 0xbfb8aa3b, v107
	v_exp_f32_e32 v110, v110
	v_mul_f32_e32 v111, v104, v105
	v_add_f32_e32 v104, 1.0, v117
	v_rcp_f32_e32 v117, v104
	v_add_f32_e32 v104, 1.0, v110
	v_rcp_f32_e32 v110, v104
	v_mov_b32_e32 v104, v96
	v_mov_b32_e32 v105, v100
	v_pk_mul_f32 v[104:105], v[104:105], v[174:175] op_sel_hi:[1,0]
	v_mul_f32_e32 v100, v109, v117
	v_mul_f32_e32 v96, 0xbfb8aa3b, v105
	v_exp_f32_e32 v96, v96
	v_mul_f32_e32 v108, v108, v100
	v_mov_b32_e32 v100, v97
	v_mul_f32_e32 v107, v107, v110
	v_add_f32_e32 v96, 1.0, v96
	v_rcp_f32_e32 v109, v96
	v_pk_mul_f32 v[96:97], v[100:101], v[174:175] op_sel_hi:[1,0]
	v_mul_f32_e32 v106, v106, v107
	v_mul_f32_e32 v100, 0xbfb8aa3b, v97
	v_exp_f32_e32 v100, v100
	v_mul_f32_e32 v101, v105, v109
	v_mul_f32_e32 v104, v104, v101
	v_mov_b32_e32 v101, v102
	v_add_f32_e32 v100, 1.0, v100
	v_rcp_f32_e32 v105, v100
	v_mov_b32_e32 v100, v98
	v_pk_mul_f32 v[100:101], v[100:101], v[174:175] op_sel_hi:[1,0]
	v_mov_b32_e32 v102, v99
	v_mul_f32_e32 v98, 0xbfb8aa3b, v101
	v_exp_f32_e32 v107, v98
	v_pk_mul_f32 v[98:99], v[102:103], v[174:175] op_sel_hi:[1,0]
	v_mul_f32_e32 v97, v97, v105
	v_mul_f32_e32 v102, 0xbfb8aa3b, v99
	v_exp_f32_e32 v102, v102
	v_add_f32_e32 v103, 1.0, v107
	v_rcp_f32_e32 v103, v103
	v_mul_f32_e32 v105, v96, v97
	v_add_f32_e32 v102, 1.0, v102
	v_rcp_f32_e32 v102, v102
	v_mul_f32_e32 v96, v101, v103
	v_mul_f32_e32 v100, v100, v96
	v_mov_b32_e32 v103, v92
	v_mul_f32_e32 v96, v99, v102
	v_mov_b32_e32 v102, v88
	v_pk_mul_f32 v[102:103], v[102:103], v[172:173] op_sel_hi:[1,0]
	v_mul_f32_e32 v99, v98, v96
	v_mul_f32_e32 v88, 0xbfb8aa3b, v103
	v_cvt_pk_bf16_f32 v96, v116, v111
	v_cvt_pk_bf16_f32 v97, v108, v106
	v_cvt_pk_bf16_f32 v98, v104, v105
	v_exp_f32_e32 v104, v88
	v_mov_b32_e32 v92, v89
	v_pk_mul_f32 v[88:89], v[92:93], v[172:173] op_sel_hi:[1,0]
	v_cvt_pk_bf16_f32 v99, v100, v99
	v_mad_i64_i32 v[100:101], s[4:5], v160, s52, v[112:113]
	v_mul_f32_e32 v92, 0xbfb8aa3b, v89
	v_exp_f32_e32 v105, v92
	v_lshl_add_u64 v[92:93], v[100:101], 0, v[114:115]
	v_add_f32_e32 v100, 1.0, v104
	v_rcp_f32_e32 v100, v100
	global_store_dwordx4 v[92:93], v[96:99], off
	v_mov_b32_e32 v93, v94
	v_add_f32_e32 v101, 1.0, v105
	v_mul_f32_e32 v92, v103, v100
	v_mul_f32_e32 v96, v102, v92
	v_mov_b32_e32 v92, v90
	v_pk_mul_f32 v[92:93], v[92:93], v[172:173] op_sel_hi:[1,0]
	v_mov_b32_e32 v94, v91
	v_mul_f32_e32 v90, 0xbfb8aa3b, v93
	v_rcp_f32_e32 v101, v101
	v_exp_f32_e32 v97, v90
	v_pk_mul_f32 v[90:91], v[94:95], v[172:173] op_sel_hi:[1,0]
	v_mul_f32_e32 v89, v89, v101
	v_mul_f32_e32 v94, 0xbfb8aa3b, v91
	v_exp_f32_e32 v94, v94
	v_mul_f32_e32 v95, v88, v89
	v_add_f32_e32 v88, 1.0, v97
	v_rcp_f32_e32 v97, v88
	v_add_f32_e32 v88, 1.0, v94
	v_rcp_f32_e32 v94, v88
	v_mov_b32_e32 v88, v80
	v_mov_b32_e32 v89, v84
	v_pk_mul_f32 v[88:89], v[88:89], v[172:173] op_sel_hi:[1,0]
	v_mul_f32_e32 v84, v93, v97
	v_mul_f32_e32 v80, 0xbfb8aa3b, v89
	v_exp_f32_e32 v80, v80
	v_mul_f32_e32 v92, v92, v84
	v_mov_b32_e32 v84, v81
	v_mul_f32_e32 v91, v91, v94
	v_add_f32_e32 v80, 1.0, v80
	v_rcp_f32_e32 v93, v80
	v_pk_mul_f32 v[80:81], v[84:85], v[172:173] op_sel_hi:[1,0]
	v_mul_f32_e32 v90, v90, v91
	v_mul_f32_e32 v84, 0xbfb8aa3b, v81
	v_exp_f32_e32 v84, v84
	v_mul_f32_e32 v85, v89, v93
	v_mul_f32_e32 v88, v88, v85
	v_mov_b32_e32 v85, v86
	v_add_f32_e32 v84, 1.0, v84
	v_rcp_f32_e32 v89, v84
	v_mov_b32_e32 v84, v82
	v_pk_mul_f32 v[84:85], v[84:85], v[172:173] op_sel_hi:[1,0]
	v_mov_b32_e32 v86, v83
	v_mul_f32_e32 v82, 0xbfb8aa3b, v85
	v_exp_f32_e32 v91, v82
	v_pk_mul_f32 v[82:83], v[86:87], v[172:173] op_sel_hi:[1,0]
	v_mul_f32_e32 v81, v81, v89
	v_mul_f32_e32 v86, 0xbfb8aa3b, v83
	v_exp_f32_e32 v86, v86
	v_add_f32_e32 v87, 1.0, v91
	v_rcp_f32_e32 v87, v87
	v_mul_f32_e32 v89, v80, v81
	v_add_f32_e32 v86, 1.0, v86
	v_rcp_f32_e32 v86, v86
	v_mul_f32_e32 v80, v85, v87
	v_mul_f32_e32 v84, v84, v80
	v_mov_b32_e32 v87, v76
	v_mul_f32_e32 v80, v83, v86
	v_mov_b32_e32 v86, v72
	v_pk_mul_f32 v[86:87], v[86:87], v[170:171] op_sel_hi:[1,0]
	v_mul_f32_e32 v83, v82, v80
	v_mul_f32_e32 v72, 0xbfb8aa3b, v87
	v_cvt_pk_bf16_f32 v80, v96, v95
	v_cvt_pk_bf16_f32 v81, v92, v90
	v_cvt_pk_bf16_f32 v82, v88, v89
	v_exp_f32_e32 v88, v72
	v_mov_b32_e32 v76, v73
	v_pk_mul_f32 v[72:73], v[76:77], v[170:171] op_sel_hi:[1,0]
	v_cvt_pk_bf16_f32 v83, v84, v83
	v_mad_i64_i32 v[84:85], s[4:5], v156, s52, v[112:113]
	v_mul_f32_e32 v76, 0xbfb8aa3b, v73
	v_exp_f32_e32 v89, v76
	v_lshl_add_u64 v[76:77], v[84:85], 0, v[114:115]
	v_add_f32_e32 v84, 1.0, v88
	v_rcp_f32_e32 v84, v84
	global_store_dwordx4 v[76:77], v[80:83], off
	v_mov_b32_e32 v77, v78
	v_add_f32_e32 v85, 1.0, v89
	v_mul_f32_e32 v76, v87, v84
	v_mul_f32_e32 v80, v86, v76
	v_mov_b32_e32 v76, v74
	v_pk_mul_f32 v[76:77], v[76:77], v[170:171] op_sel_hi:[1,0]
	v_mov_b32_e32 v78, v75
	v_mul_f32_e32 v74, 0xbfb8aa3b, v77
	v_rcp_f32_e32 v85, v85
	v_exp_f32_e32 v81, v74
	v_pk_mul_f32 v[74:75], v[78:79], v[170:171] op_sel_hi:[1,0]
	v_mul_f32_e32 v73, v73, v85
	v_mul_f32_e32 v78, 0xbfb8aa3b, v75
	v_exp_f32_e32 v78, v78
	v_mul_f32_e32 v79, v72, v73
	v_add_f32_e32 v72, 1.0, v81
	v_rcp_f32_e32 v81, v72
	v_add_f32_e32 v72, 1.0, v78
	v_rcp_f32_e32 v78, v72
	v_mov_b32_e32 v72, v64
	v_mov_b32_e32 v73, v68
	v_pk_mul_f32 v[72:73], v[72:73], v[170:171] op_sel_hi:[1,0]
	v_mul_f32_e32 v68, v77, v81
	v_mul_f32_e32 v64, 0xbfb8aa3b, v73
	v_exp_f32_e32 v64, v64
	v_mul_f32_e32 v76, v76, v68
	v_mov_b32_e32 v68, v65
	v_mul_f32_e32 v75, v75, v78
	v_add_f32_e32 v64, 1.0, v64
	v_rcp_f32_e32 v77, v64
	v_pk_mul_f32 v[64:65], v[68:69], v[170:171] op_sel_hi:[1,0]
	v_mul_f32_e32 v74, v74, v75
	v_mul_f32_e32 v68, 0xbfb8aa3b, v65
	v_exp_f32_e32 v68, v68
	v_mul_f32_e32 v69, v73, v77
	v_mul_f32_e32 v72, v72, v69
	v_mov_b32_e32 v69, v70
	v_add_f32_e32 v68, 1.0, v68
	v_rcp_f32_e32 v73, v68
	v_mov_b32_e32 v68, v66
	v_pk_mul_f32 v[68:69], v[68:69], v[170:171] op_sel_hi:[1,0]
	v_mov_b32_e32 v70, v67
	v_mul_f32_e32 v66, 0xbfb8aa3b, v69
	v_exp_f32_e32 v75, v66
	v_pk_mul_f32 v[66:67], v[70:71], v[170:171] op_sel_hi:[1,0]
	v_mul_f32_e32 v65, v65, v73
	v_mul_f32_e32 v70, 0xbfb8aa3b, v67
	v_exp_f32_e32 v70, v70
	v_add_f32_e32 v71, 1.0, v75
	v_rcp_f32_e32 v71, v71
	v_mul_f32_e32 v73, v64, v65
	v_add_f32_e32 v70, 1.0, v70
	v_rcp_f32_e32 v70, v70
	v_mul_f32_e32 v64, v69, v71
	v_mul_f32_e32 v68, v68, v64
	v_mov_b32_e32 v71, v60
	v_mul_f32_e32 v64, v67, v70
	v_mov_b32_e32 v70, v56
	v_pk_mul_f32 v[70:71], v[70:71], v[168:169] op_sel_hi:[1,0]
	v_mul_f32_e32 v67, v66, v64
	v_mul_f32_e32 v56, 0xbfb8aa3b, v71
	v_cvt_pk_bf16_f32 v64, v80, v79
	v_cvt_pk_bf16_f32 v65, v76, v74
	v_cvt_pk_bf16_f32 v66, v72, v73
	v_exp_f32_e32 v72, v56
	v_mov_b32_e32 v60, v57
	v_pk_mul_f32 v[56:57], v[60:61], v[168:169] op_sel_hi:[1,0]
	v_cvt_pk_bf16_f32 v67, v68, v67
	v_mad_i64_i32 v[68:69], s[4:5], v154, s52, v[112:113]
	v_mul_f32_e32 v60, 0xbfb8aa3b, v57
	v_exp_f32_e32 v73, v60
	v_lshl_add_u64 v[60:61], v[68:69], 0, v[114:115]
	v_add_f32_e32 v68, 1.0, v72
	v_rcp_f32_e32 v68, v68
	global_store_dwordx4 v[60:61], v[64:67], off
	v_mov_b32_e32 v61, v62
	v_add_f32_e32 v69, 1.0, v73
	v_mul_f32_e32 v60, v71, v68
	v_mul_f32_e32 v64, v70, v60
	v_mov_b32_e32 v60, v58
	v_pk_mul_f32 v[60:61], v[60:61], v[168:169] op_sel_hi:[1,0]
	v_mov_b32_e32 v62, v59
	v_mul_f32_e32 v58, 0xbfb8aa3b, v61
	v_rcp_f32_e32 v69, v69
	v_exp_f32_e32 v65, v58
	v_pk_mul_f32 v[58:59], v[62:63], v[168:169] op_sel_hi:[1,0]
	v_mul_f32_e32 v57, v57, v69
	v_mul_f32_e32 v62, 0xbfb8aa3b, v59
	v_exp_f32_e32 v62, v62
	v_mul_f32_e32 v63, v56, v57
	v_add_f32_e32 v56, 1.0, v65
	v_rcp_f32_e32 v65, v56
	v_add_f32_e32 v56, 1.0, v62
	v_rcp_f32_e32 v62, v56
	v_mov_b32_e32 v56, v48
	v_mov_b32_e32 v57, v52
	v_pk_mul_f32 v[56:57], v[56:57], v[168:169] op_sel_hi:[1,0]
	v_mul_f32_e32 v52, v61, v65
	v_mul_f32_e32 v48, 0xbfb8aa3b, v57
	v_exp_f32_e32 v48, v48
	v_mul_f32_e32 v60, v60, v52
	v_mov_b32_e32 v52, v49
	v_mul_f32_e32 v59, v59, v62
	v_add_f32_e32 v48, 1.0, v48
	v_rcp_f32_e32 v61, v48
	v_pk_mul_f32 v[48:49], v[52:53], v[168:169] op_sel_hi:[1,0]
	v_mul_f32_e32 v58, v58, v59
	v_mul_f32_e32 v52, 0xbfb8aa3b, v49
	v_exp_f32_e32 v52, v52
	v_mul_f32_e32 v53, v57, v61
	v_mul_f32_e32 v56, v56, v53
	v_mov_b32_e32 v53, v54
	v_add_f32_e32 v52, 1.0, v52
	v_rcp_f32_e32 v57, v52
	v_mov_b32_e32 v52, v50
	v_pk_mul_f32 v[52:53], v[52:53], v[168:169] op_sel_hi:[1,0]
	v_mov_b32_e32 v54, v51
	v_mul_f32_e32 v50, 0xbfb8aa3b, v53
	v_exp_f32_e32 v59, v50
	v_pk_mul_f32 v[50:51], v[54:55], v[168:169] op_sel_hi:[1,0]
	v_mul_f32_e32 v49, v49, v57
	v_mul_f32_e32 v54, 0xbfb8aa3b, v51
	v_exp_f32_e32 v54, v54
	v_add_f32_e32 v55, 1.0, v59
	v_rcp_f32_e32 v55, v55
	v_mul_f32_e32 v57, v48, v49
	v_add_f32_e32 v54, 1.0, v54
	v_rcp_f32_e32 v54, v54
	v_mul_f32_e32 v48, v53, v55
	v_mul_f32_e32 v52, v52, v48
	v_mov_b32_e32 v55, v44
	v_mul_f32_e32 v48, v51, v54
	v_mov_b32_e32 v54, v40
	v_pk_mul_f32 v[54:55], v[54:55], v[166:167] op_sel_hi:[1,0]
	v_mul_f32_e32 v51, v50, v48
	v_mul_f32_e32 v40, 0xbfb8aa3b, v55
	v_cvt_pk_bf16_f32 v48, v64, v63
	v_cvt_pk_bf16_f32 v49, v60, v58
	v_cvt_pk_bf16_f32 v50, v56, v57
	v_exp_f32_e32 v56, v40
	v_mov_b32_e32 v44, v41
	v_pk_mul_f32 v[40:41], v[44:45], v[166:167] op_sel_hi:[1,0]
	v_cvt_pk_bf16_f32 v51, v52, v51
	v_mad_i64_i32 v[52:53], s[4:5], v148, s52, v[112:113]
	v_mul_f32_e32 v44, 0xbfb8aa3b, v41
	v_exp_f32_e32 v57, v44
	v_lshl_add_u64 v[44:45], v[52:53], 0, v[114:115]
	v_add_f32_e32 v52, 1.0, v56
	v_rcp_f32_e32 v52, v52
	global_store_dwordx4 v[44:45], v[48:51], off
	v_mov_b32_e32 v45, v46
	v_add_f32_e32 v53, 1.0, v57
	v_mul_f32_e32 v44, v55, v52
	v_mul_f32_e32 v48, v54, v44
	v_mov_b32_e32 v44, v42
	v_pk_mul_f32 v[44:45], v[44:45], v[166:167] op_sel_hi:[1,0]
	v_mov_b32_e32 v46, v43
	v_mul_f32_e32 v42, 0xbfb8aa3b, v45
	v_rcp_f32_e32 v53, v53
	v_exp_f32_e32 v49, v42
	v_pk_mul_f32 v[42:43], v[46:47], v[166:167] op_sel_hi:[1,0]
	v_mul_f32_e32 v41, v41, v53
	v_mul_f32_e32 v46, 0xbfb8aa3b, v43
	v_exp_f32_e32 v46, v46
	v_mul_f32_e32 v47, v40, v41
	v_add_f32_e32 v40, 1.0, v49
	v_rcp_f32_e32 v49, v40
	v_add_f32_e32 v40, 1.0, v46
	v_rcp_f32_e32 v46, v40
	v_mov_b32_e32 v40, v32
	v_mov_b32_e32 v41, v36
	v_pk_mul_f32 v[40:41], v[40:41], v[166:167] op_sel_hi:[1,0]
	v_mul_f32_e32 v36, v45, v49
	v_mul_f32_e32 v32, 0xbfb8aa3b, v41
	v_exp_f32_e32 v32, v32
	v_mul_f32_e32 v44, v44, v36
	v_mov_b32_e32 v36, v33
	v_mul_f32_e32 v43, v43, v46
	v_add_f32_e32 v32, 1.0, v32
	v_rcp_f32_e32 v45, v32
	v_pk_mul_f32 v[32:33], v[36:37], v[166:167] op_sel_hi:[1,0]
	v_mul_f32_e32 v42, v42, v43
	v_mul_f32_e32 v36, 0xbfb8aa3b, v33
	v_exp_f32_e32 v36, v36
	v_mul_f32_e32 v37, v41, v45
	v_mul_f32_e32 v40, v40, v37
	v_mov_b32_e32 v37, v38
	v_add_f32_e32 v36, 1.0, v36
	v_rcp_f32_e32 v41, v36
	v_mov_b32_e32 v36, v34
	v_pk_mul_f32 v[36:37], v[36:37], v[166:167] op_sel_hi:[1,0]
	v_mov_b32_e32 v38, v35
	v_mul_f32_e32 v34, 0xbfb8aa3b, v37
	v_exp_f32_e32 v43, v34
	v_pk_mul_f32 v[34:35], v[38:39], v[166:167] op_sel_hi:[1,0]
	v_mul_f32_e32 v33, v33, v41
	v_mul_f32_e32 v38, 0xbfb8aa3b, v35
	v_exp_f32_e32 v38, v38
	v_add_f32_e32 v39, 1.0, v43
	v_rcp_f32_e32 v39, v39
	v_mul_f32_e32 v41, v32, v33
	v_add_f32_e32 v38, 1.0, v38
	v_rcp_f32_e32 v38, v38
	v_mul_f32_e32 v32, v37, v39
	v_mul_f32_e32 v36, v36, v32
	v_mov_b32_e32 v39, v28
	v_mul_f32_e32 v32, v35, v38
	v_mov_b32_e32 v38, v24
	v_pk_mul_f32 v[38:39], v[38:39], v[164:165] op_sel_hi:[1,0]
	v_mul_f32_e32 v35, v34, v32
	v_mul_f32_e32 v24, 0xbfb8aa3b, v39
	v_cvt_pk_bf16_f32 v32, v48, v47
	v_cvt_pk_bf16_f32 v33, v44, v42
	v_cvt_pk_bf16_f32 v34, v40, v41
	v_exp_f32_e32 v40, v24
	v_mov_b32_e32 v28, v25
	v_pk_mul_f32 v[24:25], v[28:29], v[164:165] op_sel_hi:[1,0]
	v_cvt_pk_bf16_f32 v35, v36, v35
	v_mad_i64_i32 v[36:37], s[4:5], v152, s52, v[112:113]
	v_mul_f32_e32 v28, 0xbfb8aa3b, v25
	v_exp_f32_e32 v41, v28
	v_lshl_add_u64 v[28:29], v[36:37], 0, v[114:115]
	v_add_f32_e32 v36, 1.0, v40
	v_rcp_f32_e32 v36, v36
	global_store_dwordx4 v[28:29], v[32:35], off
	v_mov_b32_e32 v29, v30
	v_add_f32_e32 v37, 1.0, v41
	v_mul_f32_e32 v28, v39, v36
	v_mul_f32_e32 v32, v38, v28
	v_mov_b32_e32 v28, v26
	v_pk_mul_f32 v[28:29], v[28:29], v[164:165] op_sel_hi:[1,0]
	v_mov_b32_e32 v30, v27
	v_mul_f32_e32 v26, 0xbfb8aa3b, v29
	v_rcp_f32_e32 v37, v37
	v_exp_f32_e32 v33, v26
	v_pk_mul_f32 v[26:27], v[30:31], v[164:165] op_sel_hi:[1,0]
	v_mul_f32_e32 v25, v25, v37
	v_mul_f32_e32 v30, 0xbfb8aa3b, v27
	v_exp_f32_e32 v30, v30
	v_mul_f32_e32 v31, v24, v25
	v_add_f32_e32 v24, 1.0, v33
	v_rcp_f32_e32 v33, v24
	v_add_f32_e32 v24, 1.0, v30
	v_rcp_f32_e32 v30, v24
	v_mov_b32_e32 v24, v16
	v_mov_b32_e32 v25, v20
	v_pk_mul_f32 v[24:25], v[24:25], v[164:165] op_sel_hi:[1,0]
	v_mul_f32_e32 v20, v29, v33
	v_mul_f32_e32 v16, 0xbfb8aa3b, v25
	v_exp_f32_e32 v16, v16
	v_mul_f32_e32 v28, v28, v20
	v_mov_b32_e32 v20, v17
	v_mul_f32_e32 v27, v27, v30
	v_add_f32_e32 v16, 1.0, v16
	v_rcp_f32_e32 v29, v16
	v_pk_mul_f32 v[16:17], v[20:21], v[164:165] op_sel_hi:[1,0]
	v_mul_f32_e32 v26, v26, v27
	v_mul_f32_e32 v20, 0xbfb8aa3b, v17
	v_exp_f32_e32 v20, v20
	v_mul_f32_e32 v21, v25, v29
	v_mul_f32_e32 v24, v24, v21
	v_mov_b32_e32 v21, v22
	v_add_f32_e32 v20, 1.0, v20
	v_rcp_f32_e32 v25, v20
	v_mov_b32_e32 v20, v18
	v_pk_mul_f32 v[20:21], v[20:21], v[164:165] op_sel_hi:[1,0]
	v_mov_b32_e32 v22, v19
	v_mul_f32_e32 v18, 0xbfb8aa3b, v21
	v_exp_f32_e32 v27, v18
	v_pk_mul_f32 v[18:19], v[22:23], v[164:165] op_sel_hi:[1,0]
	v_mul_f32_e32 v17, v17, v25
	v_mul_f32_e32 v22, 0xbfb8aa3b, v19
	v_exp_f32_e32 v22, v22
	v_add_f32_e32 v23, 1.0, v27
	v_rcp_f32_e32 v23, v23
	v_mul_f32_e32 v25, v16, v17
	v_add_f32_e32 v22, 1.0, v22
	v_rcp_f32_e32 v22, v22
	v_mul_f32_e32 v16, v21, v23
	v_mul_f32_e32 v20, v20, v16
	v_mov_b32_e32 v23, v12
	v_mul_f32_e32 v16, v19, v22
	v_mov_b32_e32 v22, v8
	v_pk_mul_f32 v[22:23], v[22:23], v[158:159] op_sel_hi:[1,0]
	v_mul_f32_e32 v19, v18, v16
	v_mul_f32_e32 v8, 0xbfb8aa3b, v23
	v_cvt_pk_bf16_f32 v16, v32, v31
	v_cvt_pk_bf16_f32 v17, v28, v26
	v_cvt_pk_bf16_f32 v18, v24, v25
	v_exp_f32_e32 v24, v8
	v_mov_b32_e32 v12, v9
	v_pk_mul_f32 v[8:9], v[12:13], v[158:159] op_sel_hi:[1,0]
	v_cvt_pk_bf16_f32 v19, v20, v19
	v_mad_i64_i32 v[20:21], s[4:5], v150, s52, v[112:113]
	v_mul_f32_e32 v12, 0xbfb8aa3b, v9
	v_exp_f32_e32 v25, v12
	v_lshl_add_u64 v[12:13], v[20:21], 0, v[114:115]
	v_add_f32_e32 v20, 1.0, v24
	v_rcp_f32_e32 v20, v20
	global_store_dwordx4 v[12:13], v[16:19], off
	v_mov_b32_e32 v13, v14
	v_add_f32_e32 v21, 1.0, v25
	v_mul_f32_e32 v12, v23, v20
	v_mul_f32_e32 v16, v22, v12
	v_mov_b32_e32 v12, v10
	v_pk_mul_f32 v[12:13], v[12:13], v[158:159] op_sel_hi:[1,0]
	v_mov_b32_e32 v14, v11
	v_mul_f32_e32 v10, 0xbfb8aa3b, v13
	v_rcp_f32_e32 v21, v21
	v_exp_f32_e32 v17, v10
	v_pk_mul_f32 v[10:11], v[14:15], v[158:159] op_sel_hi:[1,0]
	v_mul_f32_e32 v9, v9, v21
	v_mul_f32_e32 v14, 0xbfb8aa3b, v11
	v_exp_f32_e32 v14, v14
	v_mul_f32_e32 v15, v8, v9
	v_add_f32_e32 v8, 1.0, v17
	v_rcp_f32_e32 v17, v8
	v_add_f32_e32 v8, 1.0, v14
	v_rcp_f32_e32 v14, v8
	v_mov_b32_e32 v8, v0
	v_mov_b32_e32 v9, v4
	v_pk_mul_f32 v[8:9], v[8:9], v[158:159] op_sel_hi:[1,0]
	v_mul_f32_e32 v4, v13, v17
	v_mul_f32_e32 v0, 0xbfb8aa3b, v9
	v_exp_f32_e32 v0, v0
	v_mul_f32_e32 v12, v12, v4
	v_mov_b32_e32 v4, v1
	v_mul_f32_e32 v11, v11, v14
	v_add_f32_e32 v0, 1.0, v0
	v_rcp_f32_e32 v13, v0
	v_pk_mul_f32 v[0:1], v[4:5], v[158:159] op_sel_hi:[1,0]
	v_mul_f32_e32 v10, v10, v11
	v_mul_f32_e32 v4, 0xbfb8aa3b, v1
	v_exp_f32_e32 v4, v4
	v_mul_f32_e32 v5, v9, v13
	v_mul_f32_e32 v8, v8, v5
	v_mov_b32_e32 v5, v6
	v_add_f32_e32 v4, 1.0, v4
	v_rcp_f32_e32 v9, v4
	v_mov_b32_e32 v4, v2
	v_pk_mul_f32 v[4:5], v[4:5], v[158:159] op_sel_hi:[1,0]
	v_mov_b32_e32 v6, v3
	v_mul_f32_e32 v2, 0xbfb8aa3b, v5
	v_exp_f32_e32 v11, v2
	v_pk_mul_f32 v[2:3], v[6:7], v[158:159] op_sel_hi:[1,0]
	v_mul_f32_e32 v1, v1, v9
	v_mul_f32_e32 v6, 0xbfb8aa3b, v3
	v_exp_f32_e32 v6, v6
	v_add_f32_e32 v7, 1.0, v11
	v_rcp_f32_e32 v7, v7
	v_mul_f32_e32 v9, v0, v1
	v_add_f32_e32 v6, 1.0, v6
	v_rcp_f32_e32 v6, v6
	v_mul_f32_e32 v0, v5, v7
	v_mul_f32_e32 v4, v4, v0
	v_mul_f32_e32 v0, v3, v6
	v_mul_f32_e32 v3, v2, v0
	v_cvt_pk_bf16_f32 v0, v16, v15
	v_cvt_pk_bf16_f32 v1, v12, v10
	v_cvt_pk_bf16_f32 v2, v8, v9
	v_cvt_pk_bf16_f32 v3, v4, v3
	v_mad_i64_i32 v[4:5], s[4:5], v146, s52, v[112:113]
	v_lshl_add_u64 v[4:5], v[4:5], 0, v[114:115]
	s_mov_b64 s[4:5], -1
	global_store_dwordx4 v[4:5], v[0:3], off
	s_cbranch_vccnz .LBB0_479
	s_andn2_b64 vcc, exec, s[16:17]
	s_cbranch_vccnz .LBB0_478
	s_barrier
	s_branch .LBB0_478

.LBB0_1039:
	s_mov_b32 s62, -1
	s_or_b64 exec, exec, s[6:7]
	v_readlane_b32 s6, v254, 6
	s_mov_b64 s[4:5], s[0:1]
	s_waitcnt lgkmcnt(0)
	v_mov_b32_e32 v0, v202
	v_mov_b32_e32 v8, v202
	v_readlane_b32 s7, v254, 7
	s_barrier
	s_andn2_b64 vcc, exec, s[6:7]
	v_readfirstlane_b32 s13, v8
	s_cbranch_vccnz .LBB0_1055
	v_lshlrev_b32_e32 v0, 4, v8
	v_add_u32_e32 v1, 0x2000, v0
	v_ashrrev_i32_e32 v2, 31, v1
	v_lshrrev_b32_e32 v2, 22, v2
	v_add_u32_e32 v2, v1, v2
	v_ashrrev_i32_e32 v9, 10, v2
	v_mul_i32_i24_e32 v2, 0x400, v9
	v_sub_u32_e32 v1, v1, v2
	v_lshrrev_b32_e32 v2, 4, v1
	v_bitop3_b32 v1, v2, v1, 32 bitop3:0x6c
	v_ashrrev_i32_e32 v2, 31, v1
	v_lshrrev_b32_e32 v2, 26, v2
	v_add_u32_e32 v2, v1, v2
	v_lshlrev_b32_e32 v3, 3, v9
	v_ashrrev_i32_e32 v10, 6, v2
	v_and_b32_e32 v3, -16, v3
	v_add_u32_e32 v3, v10, v3
	s_load_dwordx2 s[6:7], s[4:5], 0xa0
	v_and_b32_e32 v4, 3, v10
	s_mov_b32 s4, 0x1fffe0
	v_lshrrev_b32_e32 v5, 2, v3
	v_lshlrev_b32_e32 v6, 1, v3
	v_and_b32_e32 v2, 0xc0, v2
	v_and_or_b32 v4, v3, s4, v4
	v_and_b32_e32 v5, 4, v5
	v_and_b32_e32 v6, 24, v6
	v_sub_u32_e32 v1, v1, v2
	v_mov_b32_e32 v2, 1
	v_or3_b32 v4, v4, v5, v6
	v_lshlrev_b32_e32 v5, 5, v9
	v_ashrrev_i16_sdwa v1, v2, sext(v1) dst_sel:DWORD dst_unused:UNUSED_PAD src0_sel:DWORD src1_sel:BYTE_0
	v_and_b32_e32 v5, 32, v5
	v_bfe_i32 v11, v1, 0, 16
	v_add_lshl_u32 v1, v5, v11, 1
	v_lshl_add_u32 v128, v4, 11, v1
	v_lshl_add_u32 v130, v3, 11, v1
	v_bfe_i32 v1, v8, 27, 1
	v_lshrrev_b32_e32 v1, 22, v1
	v_add_u32_e32 v1, v0, v1
	v_and_b32_e32 v1, 0xfffffc00, v1
	v_sub_u32_e32 v0, v0, v1
	v_lshrrev_b32_e32 v1, 4, v0
	v_ashrrev_i32_e32 v3, 31, v8
	v_bitop3_b32 v0, v1, v0, 32 bitop3:0x6c
	v_lshrrev_b32_e32 v3, 26, v3
	v_ashrrev_i32_e32 v1, 31, v0
	v_add_u32_e32 v3, v8, v3
	v_lshrrev_b32_e32 v1, 26, v1
	v_ashrrev_i32_e32 v13, 6, v3
	s_waitcnt lgkmcnt(0)
	s_add_u32 s14, s6, 0x4800000
	v_add_u32_e32 v1, v0, v1
	v_lshlrev_b32_e32 v3, 3, v13
	s_addc_u32 s15, s7, 0
	v_ashrrev_i32_e32 v12, 6, v1
	v_and_b32_e32 v3, -16, v3
	s_add_u32 s20, s6, 0x3080000
	v_add_u32_e32 v3, v12, v3
	v_and_b32_e32 v4, 3, v12
	s_addc_u32 s38, s7, 0
	v_and_or_b32 v4, v3, s4, v4
	s_lshr_b32 s4, s21, 29
	s_add_i32 s4, s2, s4
	s_ashr_i32 s24, s13, 6
	s_ashr_i32 s5, s4, 3
	s_and_b32 s4, s4, -8
	s_ashr_i32 s26, s13, 8
	s_lshl_b32 s39, s24, 10
	s_sub_i32 s4, s2, s4
	s_cmp_lt_i32 s4, 0
	s_movk_i32 s40, 0x161
	s_cselect_b32 s8, s40, 0x160
	s_mul_i32 s4, s4, s8
	s_add_i32 s4, s4, s5
	s_mul_hi_i32 s5, s4, 0x2e8ba2e9
	s_lshr_b32 s8, s5, 31
	s_ashr_i32 s5, s5, 5
	s_add_i32 s5, s5, s8
	s_lshl_b32 s8, s5, 3
	s_mulk_i32 s5, 0xb0
	s_sub_i32 s4, s4, s5
	s_sext_i32_i16 s5, s4
	s_bfe_u32 s5, s5, 0x3001c
	s_add_i32 s5, s4, s5
	s_sext_i32_i16 s9, s5
	s_and_b32 s5, s5, 0xfff8
	s_sub_i32 s4, s4, s5
	s_sext_i32_i16 s4, s4
	v_lshrrev_b32_e32 v5, 2, v3
	v_lshlrev_b32_e32 v6, 1, v3
	v_and_b32_e32 v1, 0xc0, v1
	s_lshr_b32 s12, s9, 3
	s_add_i32 s8, s8, s4
	v_and_b32_e32 v5, 4, v5
	v_and_b32_e32 v6, 24, v6
	v_sub_u32_e32 v0, v0, v1
	s_ashr_i32 s9, s8, 31
	s_bfe_i64 s[4:5], s[12:13], 0x100000
	v_or3_b32 v4, v4, v5, v6
	v_lshlrev_b32_e32 v5, 5, v13
	v_ashrrev_i16_sdwa v0, v2, sext(v0) dst_sel:DWORD dst_unused:UNUSED_PAD src0_sel:DWORD src1_sel:BYTE_0
	s_lshl_b64 s[10:11], s[8:9], 19
	s_lshl_b64 s[4:5], s[4:5], 19
	v_and_b32_e32 v5, 32, v5
	v_bfe_i32 v14, v0, 0, 16
	s_add_u32 s4, s20, s4
	v_add_lshl_u32 v0, v5, v14, 1
	s_addc_u32 s5, s38, s5
	s_add_i32 s41, s39, 0
	v_lshl_add_u32 v132, v4, 11, v0
	s_add_i32 m0, s41, 0x10000
	v_lshl_add_u32 v134, v3, 11, v0
	global_load_lds_dwordx4 v132, s[4:5]
	s_add_i32 m0, s41, 0x12000
	s_add_u32 s16, s4, 0x40000
	global_load_lds_dwordx4 v128, s[4:5]
	s_addc_u32 s17, s5, 0
	s_add_i32 m0, s41, 0x14000
	v_mov_b32_e32 v133, 0
	global_load_lds_dwordx4 v132, s[16:17]
	s_add_i32 m0, s41, 0x16000
	s_add_u32 s10, s14, s10
	s_addc_u32 s11, s15, s11
	s_add_i32 s42, s41, 0x2000
	global_load_lds_dwordx4 v128, s[16:17]
	s_mov_b32 m0, s41
	s_add_u32 s16, s10, 0x40000
	global_load_lds_dwordx4 v134, s[10:11]
	s_mov_b32 m0, s42
	s_addc_u32 s17, s11, 0
	s_add_i32 s43, s41, 0x4000
	global_load_lds_dwordx4 v130, s[10:11]
	s_mov_b32 m0, s43
	s_add_i32 s44, s41, 0x6000
	global_load_lds_dwordx4 v134, s[16:17]
	s_mov_b32 m0, s44
	v_mov_b32_e32 v129, v133
	global_load_lds_dwordx4 v130, s[16:17]
	v_mov_b32_e32 v135, v133
	v_mov_b32_e32 v131, v133
	s_cmp_eq_u32 s26, 1
	s_mov_b32 s45, 0
	v_lshl_add_u64 v[6:7], s[4:5], 0, v[132:133]
	v_lshl_add_u64 v[4:5], s[4:5], 0, v[128:129]
	v_lshl_add_u64 v[0:1], s[10:11], 0, v[134:135]
	s_cselect_b64 s[16:17], -1, 0
	s_cmp_lg_u32 s26, 1
	v_lshl_add_u64 v[2:3], s[10:11], 0, v[130:131]
	s_cbranch_scc1 .LBB0_1042
	s_barrier

.LBB0_1051:
	v_lshl_add_u32 v162, s8, 8, v159
	s_cmp_eq_u32 s8, s62
	s_cbranch_scc1 .Lrstd_reuse_p9
	s_mov_b64 s[60:61], 0x2000
	v_lshlrev_b32_e32 v204, 6, v162
	v_mov_b32_e32 v205, 0
	v_mbcnt_lo_u32_b32 v248, -1, 0
	v_mbcnt_hi_u32_b32 v248, -1, v248
	v_xor_b32_e32 v248, 16, v248
	v_lshl_add_u64 v[204:205], v[136:137], 0, v[204:205]
	v_lshlrev_b32_e32 v248, 2, v248
	v_lshl_add_u64 v[206:207], v[204:205], 0, s[60:61]
	global_load_dwordx4 v[208:211], v[204:205], off
	global_load_dwordx4 v[212:215], v[204:205], off offset:1024
	global_load_dwordx4 v[216:219], v[204:205], off offset:2048
	global_load_dwordx4 v[220:223], v[204:205], off offset:3072
	global_load_dwordx4 v[224:227], v[206:207], off
	global_load_dwordx4 v[228:231], v[206:207], off offset:1024
	global_load_dwordx4 v[232:235], v[206:207], off offset:2048
	global_load_dwordx4 v[236:239], v[206:207], off offset:3072
	s_waitcnt vmcnt(0)
	v_add_f32_e32 v208, v208, v209
	v_add_f32_e32 v210, v210, v211
	v_add_f32_e32 v212, v212, v213
	v_add_f32_e32 v214, v214, v215
	v_add_f32_e32 v216, v216, v217
	v_add_f32_e32 v218, v218, v219
	v_add_f32_e32 v220, v220, v221
	v_add_f32_e32 v222, v222, v223
	v_add_f32_e32 v224, v224, v225
	v_add_f32_e32 v226, v226, v227
	v_add_f32_e32 v228, v228, v229
	v_add_f32_e32 v230, v230, v231
	v_add_f32_e32 v232, v232, v233
	v_add_f32_e32 v234, v234, v235
	v_add_f32_e32 v236, v236, v237
	v_add_f32_e32 v238, v238, v239
	v_add_f32_e32 v208, v208, v210
	v_add_f32_e32 v212, v212, v214
	v_add_f32_e32 v216, v216, v218
	v_add_f32_e32 v220, v220, v222
	v_add_f32_e32 v224, v224, v226
	v_add_f32_e32 v228, v228, v230
	v_add_f32_e32 v232, v232, v234
	v_add_f32_e32 v236, v236, v238
	ds_bpermute_b32 v209, v248, v208
	ds_bpermute_b32 v213, v248, v212
	ds_bpermute_b32 v217, v248, v216
	ds_bpermute_b32 v221, v248, v220
	ds_bpermute_b32 v225, v248, v224
	ds_bpermute_b32 v229, v248, v228
	ds_bpermute_b32 v233, v248, v232
	ds_bpermute_b32 v237, v248, v236
	s_waitcnt lgkmcnt(0)
	v_add_f32_e32 v208, v208, v209
	v_add_f32_e32 v212, v212, v213
	v_add_f32_e32 v216, v216, v217
	v_add_f32_e32 v220, v220, v221
	v_add_f32_e32 v224, v224, v225
	v_add_f32_e32 v228, v228, v229
	v_add_f32_e32 v232, v232, v233
	v_add_f32_e32 v236, v236, v237
	v_mov_b32_e32 v209, v208
	v_mov_b32_e32 v213, v212
	v_mov_b32_e32 v217, v216
	v_mov_b32_e32 v221, v220
	v_mov_b32_e32 v225, v224
	v_mov_b32_e32 v229, v228
	v_mov_b32_e32 v233, v232
	v_mov_b32_e32 v237, v236
	s_nop 1
	v_permlane32_swap_b32_e32 v208, v209
	v_permlane32_swap_b32_e32 v212, v213
	v_permlane32_swap_b32_e32 v216, v217
	v_permlane32_swap_b32_e32 v220, v221
	v_permlane32_swap_b32_e32 v224, v225
	v_permlane32_swap_b32_e32 v228, v229
	v_permlane32_swap_b32_e32 v232, v233
	v_permlane32_swap_b32_e32 v236, v237
	v_add_f32_e32 v208, v208, v209
	v_add_f32_e32 v212, v212, v213
	v_add_f32_e32 v216, v216, v217
	v_add_f32_e32 v220, v220, v221
	v_add_f32_e32 v224, v224, v225
	v_add_f32_e32 v228, v228, v229
	v_add_f32_e32 v232, v232, v233
	v_add_f32_e32 v236, v236, v237
	v_fmamk_f32 v208, v208, 0x3a800000, v175
	v_fmamk_f32 v212, v212, 0x3a800000, v175
	v_fmamk_f32 v216, v216, 0x3a800000, v175
	v_fmamk_f32 v220, v220, 0x3a800000, v175
	v_fmamk_f32 v224, v224, 0x3a800000, v175
	v_fmamk_f32 v228, v228, 0x3a800000, v175
	v_fmamk_f32 v232, v232, 0x3a800000, v175
	v_fmamk_f32 v236, v236, 0x3a800000, v175
	v_rsq_f32_e32 v176, v208
	v_rsq_f32_e32 v174, v212
	v_rsq_f32_e32 v172, v216
	v_rsq_f32_e32 v170, v220
	v_rsq_f32_e32 v168, v224
	v_rsq_f32_e32 v166, v228
	v_rsq_f32_e32 v164, v232
	v_rsq_f32_e32 v158, v236
	s_nop 0
	v_mov_b32_e32 v240, v176
	v_mov_b32_e32 v241, v174
	v_mov_b32_e32 v242, v172
	v_mov_b32_e32 v243, v170
	v_mov_b32_e32 v244, v168
	v_mov_b32_e32 v245, v166
	v_mov_b32_e32 v246, v164
	v_mov_b32_e32 v247, v158
	s_mov_b32 s62, s8
	s_branch .Lrstd_done_p9

.Lrstd_done_p9:
	v_or_b32_e32 v160, 16, v162
	v_or_b32_e32 v156, 32, v162
	v_or_b32_e32 v154, 48, v162
	v_add_u32_e32 v148, 0x80, v162
	s_nop 0
	v_add_u32_e32 v152, 0x90, v162
	v_add_u32_e32 v150, 0xa0, v162
	s_nop 0
	s_nop 1
	v_add_u32_e32 v146, 0xb0, v162
	s_waitcnt lgkmcnt(0)
	s_waitcnt vmcnt(1)
	s_waitcnt lgkmcnt(0)
	s_waitcnt lgkmcnt(0)
	s_waitcnt vmcnt(0)
	v_mov_b32_e32 v178, v120
	s_waitcnt lgkmcnt(0)
	s_waitcnt lgkmcnt(0)
	v_mov_b32_e32 v179, v124
	v_pk_mul_f32 v[178:179], v[178:179], v[176:177] op_sel_hi:[1,0]
	v_mov_b32_e32 v124, v121
	v_mul_f32_e32 v120, 0xbfb8aa3b, v179
	v_exp_f32_e32 v147, v120
	v_pk_mul_f32 v[120:121], v[124:125], v[176:177] op_sel_hi:[1,0]
	s_andn2_b64 vcc, exec, s[6:7]
	v_mul_f32_e32 v124, 0xbfb8aa3b, v121
	v_exp_f32_e32 v125, v124
	v_add_f32_e32 v147, 1.0, v147
	v_rcp_f32_e32 v147, v147
	v_lshl_or_b32 v124, s33, 7, v167
	v_add_f32_e32 v125, 1.0, v125
	v_rcp_f32_e32 v149, v125
	v_mul_f32_e32 v147, v179, v147
	v_mul_f32_e32 v147, v178, v147
	v_mov_b32_e32 v178, v122
	v_mov_b32_e32 v179, v126
	v_pk_mul_f32 v[178:179], v[178:179], v[176:177] op_sel_hi:[1,0]
	v_mov_b32_e32 v126, v123
	v_mul_f32_e32 v122, 0xbfb8aa3b, v179
	v_mul_f32_e32 v121, v121, v149
	v_exp_f32_e32 v149, v122
	v_pk_mul_f32 v[122:123], v[126:127], v[176:177] op_sel_hi:[1,0]
	v_mul_f32_e32 v127, v120, v121
	v_mul_f32_e32 v126, 0xbfb8aa3b, v123
	v_exp_f32_e32 v126, v126
	v_add_f32_e32 v120, 1.0, v149
	v_rcp_f32_e32 v149, v120
	v_mov_b32_e32 v121, v116
	v_add_f32_e32 v120, 1.0, v126
	v_rcp_f32_e32 v126, v120
	v_mov_b32_e32 v120, v112
	v_pk_mul_f32 v[120:121], v[120:121], v[176:177] op_sel_hi:[1,0]
	v_mul_f32_e32 v116, v179, v149
	v_mul_f32_e32 v112, 0xbfb8aa3b, v121
	v_exp_f32_e32 v112, v112
	v_mul_f32_e32 v149, v178, v116
	v_mov_b32_e32 v116, v113
	v_mul_f32_e32 v123, v123, v126
	v_add_f32_e32 v112, 1.0, v112
	v_rcp_f32_e32 v126, v112
	v_pk_mul_f32 v[112:113], v[116:117], v[176:177] op_sel_hi:[1,0]
	v_mul_f32_e32 v122, v122, v123
	v_mul_f32_e32 v116, 0xbfb8aa3b, v113
	v_exp_f32_e32 v116, v116
	v_mul_f32_e32 v117, v121, v126
	v_mul_f32_e32 v120, v120, v117
	v_mov_b32_e32 v117, v118
	v_add_f32_e32 v116, 1.0, v116
	v_rcp_f32_e32 v121, v116
	v_mov_b32_e32 v116, v114
	v_pk_mul_f32 v[116:117], v[116:117], v[176:177] op_sel_hi:[1,0]
	v_mov_b32_e32 v118, v115
	v_mul_f32_e32 v114, 0xbfb8aa3b, v117
	v_exp_f32_e32 v123, v114
	v_pk_mul_f32 v[114:115], v[118:119], v[176:177] op_sel_hi:[1,0]
	v_mul_f32_e32 v113, v113, v121
	v_mul_f32_e32 v118, 0xbfb8aa3b, v115
	v_exp_f32_e32 v118, v118
	v_add_f32_e32 v119, 1.0, v123
	v_rcp_f32_e32 v119, v119
	v_mul_f32_e32 v112, v112, v113
	v_add_f32_e32 v118, 1.0, v118
	v_rcp_f32_e32 v118, v118
	v_mul_f32_e32 v113, v117, v119
	v_mul_f32_e32 v113, v116, v113
	v_cvt_pk_bf16_f32 v116, v147, v127
	v_cvt_pk_bf16_f32 v117, v149, v122
	v_mov_b32_e32 v122, v104
	v_mov_b32_e32 v123, v108
	v_mul_f32_e32 v115, v115, v118
	v_pk_mul_f32 v[122:123], v[122:123], v[174:175] op_sel_hi:[1,0]
	v_ashrrev_i32_e32 v125, 31, v124
	v_mul_f32_e32 v114, v114, v115
	v_mul_f32_e32 v104, 0xbfb8aa3b, v123
	v_cvt_pk_bf16_f32 v118, v120, v112
	v_cvt_pk_bf16_f32 v119, v113, v114
	v_lshlrev_b64 v[114:115], 1, v[124:125]
	v_exp_f32_e32 v124, v104
	v_mov_b32_e32 v108, v105
	v_mov_b64_e32 v[112:113], s[22:23]
	v_pk_mul_f32 v[104:105], v[108:109], v[174:175] op_sel_hi:[1,0]
	v_mad_i64_i32 v[120:121], s[4:5], v162, s51, v[112:113]
	v_mul_f32_e32 v108, 0xbfb8aa3b, v105
	v_exp_f32_e32 v125, v108
	v_lshl_add_u64 v[108:109], v[120:121], 0, v[114:115]
	v_add_f32_e32 v120, 1.0, v124
	v_rcp_f32_e32 v120, v120
	global_store_dwordx4 v[108:109], v[116:119], off
	v_mov_b32_e32 v109, v110
	v_add_f32_e32 v121, 1.0, v125
	v_mul_f32_e32 v108, v123, v120
	v_mul_f32_e32 v116, v122, v108
	v_mov_b32_e32 v108, v106
	v_pk_mul_f32 v[108:109], v[108:109], v[174:175] op_sel_hi:[1,0]
	v_mov_b32_e32 v110, v107
	v_mul_f32_e32 v106, 0xbfb8aa3b, v109
	v_rcp_f32_e32 v121, v121
	v_exp_f32_e32 v117, v106
	v_pk_mul_f32 v[106:107], v[110:111], v[174:175] op_sel_hi:[1,0]
	v_mul_f32_e32 v105, v105, v121
	v_mul_f32_e32 v110, 0xbfb8aa3b, v107
	v_exp_f32_e32 v110, v110
	v_mul_f32_e32 v111, v104, v105
	v_add_f32_e32 v104, 1.0, v117
	v_rcp_f32_e32 v117, v104
	v_add_f32_e32 v104, 1.0, v110
	v_rcp_f32_e32 v110, v104
	v_mov_b32_e32 v104, v96
	v_mov_b32_e32 v105, v100
	v_pk_mul_f32 v[104:105], v[104:105], v[174:175] op_sel_hi:[1,0]
	v_mul_f32_e32 v100, v109, v117
	v_mul_f32_e32 v96, 0xbfb8aa3b, v105
	v_exp_f32_e32 v96, v96
	v_mul_f32_e32 v108, v108, v100
	v_mov_b32_e32 v100, v97
	v_mul_f32_e32 v107, v107, v110
	v_add_f32_e32 v96, 1.0, v96
	v_rcp_f32_e32 v109, v96
	v_pk_mul_f32 v[96:97], v[100:101], v[174:175] op_sel_hi:[1,0]
	v_mul_f32_e32 v106, v106, v107
	v_mul_f32_e32 v100, 0xbfb8aa3b, v97
	v_exp_f32_e32 v100, v100
	v_mul_f32_e32 v101, v105, v109
	v_mul_f32_e32 v104, v104, v101
	v_mov_b32_e32 v101, v102
	v_add_f32_e32 v100, 1.0, v100
	v_rcp_f32_e32 v105, v100
	v_mov_b32_e32 v100, v98
	v_pk_mul_f32 v[100:101], v[100:101], v[174:175] op_sel_hi:[1,0]
	v_mov_b32_e32 v102, v99
	v_mul_f32_e32 v98, 0xbfb8aa3b, v101
	v_exp_f32_e32 v107, v98
	v_pk_mul_f32 v[98:99], v[102:103], v[174:175] op_sel_hi:[1,0]
	v_mul_f32_e32 v97, v97, v105
	v_mul_f32_e32 v102, 0xbfb8aa3b, v99
	v_exp_f32_e32 v102, v102
	v_add_f32_e32 v103, 1.0, v107
	v_rcp_f32_e32 v103, v103
	v_mul_f32_e32 v105, v96, v97
	v_add_f32_e32 v102, 1.0, v102
	v_rcp_f32_e32 v102, v102
	v_mul_f32_e32 v96, v101, v103
	v_mul_f32_e32 v100, v100, v96
	v_mov_b32_e32 v103, v92
	v_mul_f32_e32 v96, v99, v102
	v_mov_b32_e32 v102, v88
	v_pk_mul_f32 v[102:103], v[102:103], v[172:173] op_sel_hi:[1,0]
	v_mul_f32_e32 v99, v98, v96
	v_mul_f32_e32 v88, 0xbfb8aa3b, v103
	v_cvt_pk_bf16_f32 v96, v116, v111
	v_cvt_pk_bf16_f32 v97, v108, v106
	v_cvt_pk_bf16_f32 v98, v104, v105
	v_exp_f32_e32 v104, v88
	v_mov_b32_e32 v92, v89
	v_pk_mul_f32 v[88:89], v[92:93], v[172:173] op_sel_hi:[1,0]
	v_cvt_pk_bf16_f32 v99, v100, v99
	v_mad_i64_i32 v[100:101], s[4:5], v160, s51, v[112:113]
	v_mul_f32_e32 v92, 0xbfb8aa3b, v89
	v_exp_f32_e32 v105, v92
	v_lshl_add_u64 v[92:93], v[100:101], 0, v[114:115]
	v_add_f32_e32 v100, 1.0, v104
	v_rcp_f32_e32 v100, v100
	global_store_dwordx4 v[92:93], v[96:99], off
	v_mov_b32_e32 v93, v94
	v_add_f32_e32 v101, 1.0, v105
	v_mul_f32_e32 v92, v103, v100
	v_mul_f32_e32 v96, v102, v92
	v_mov_b32_e32 v92, v90
	v_pk_mul_f32 v[92:93], v[92:93], v[172:173] op_sel_hi:[1,0]
	v_mov_b32_e32 v94, v91
	v_mul_f32_e32 v90, 0xbfb8aa3b, v93
	v_rcp_f32_e32 v101, v101
	v_exp_f32_e32 v97, v90
	v_pk_mul_f32 v[90:91], v[94:95], v[172:173] op_sel_hi:[1,0]
	v_mul_f32_e32 v89, v89, v101
	v_mul_f32_e32 v94, 0xbfb8aa3b, v91
	v_exp_f32_e32 v94, v94
	v_mul_f32_e32 v95, v88, v89
	v_add_f32_e32 v88, 1.0, v97
	v_rcp_f32_e32 v97, v88
	v_add_f32_e32 v88, 1.0, v94
	v_rcp_f32_e32 v94, v88
	v_mov_b32_e32 v88, v80
	v_mov_b32_e32 v89, v84
	v_pk_mul_f32 v[88:89], v[88:89], v[172:173] op_sel_hi:[1,0]
	v_mul_f32_e32 v84, v93, v97
	v_mul_f32_e32 v80, 0xbfb8aa3b, v89
	v_exp_f32_e32 v80, v80
	v_mul_f32_e32 v92, v92, v84
	v_mov_b32_e32 v84, v81
	v_mul_f32_e32 v91, v91, v94
	v_add_f32_e32 v80, 1.0, v80
	v_rcp_f32_e32 v93, v80
	v_pk_mul_f32 v[80:81], v[84:85], v[172:173] op_sel_hi:[1,0]
	v_mul_f32_e32 v90, v90, v91
	v_mul_f32_e32 v84, 0xbfb8aa3b, v81
	v_exp_f32_e32 v84, v84
	v_mul_f32_e32 v85, v89, v93
	v_mul_f32_e32 v88, v88, v85
	v_mov_b32_e32 v85, v86
	v_add_f32_e32 v84, 1.0, v84
	v_rcp_f32_e32 v89, v84
	v_mov_b32_e32 v84, v82
	v_pk_mul_f32 v[84:85], v[84:85], v[172:173] op_sel_hi:[1,0]
	v_mov_b32_e32 v86, v83
	v_mul_f32_e32 v82, 0xbfb8aa3b, v85
	v_exp_f32_e32 v91, v82
	v_pk_mul_f32 v[82:83], v[86:87], v[172:173] op_sel_hi:[1,0]
	v_mul_f32_e32 v81, v81, v89
	v_mul_f32_e32 v86, 0xbfb8aa3b, v83
	v_exp_f32_e32 v86, v86
	v_add_f32_e32 v87, 1.0, v91
	v_rcp_f32_e32 v87, v87
	v_mul_f32_e32 v89, v80, v81
	v_add_f32_e32 v86, 1.0, v86
	v_rcp_f32_e32 v86, v86
	v_mul_f32_e32 v80, v85, v87
	v_mul_f32_e32 v84, v84, v80
	v_mov_b32_e32 v87, v76
	v_mul_f32_e32 v80, v83, v86
	v_mov_b32_e32 v86, v72
	v_pk_mul_f32 v[86:87], v[86:87], v[170:171] op_sel_hi:[1,0]
	v_mul_f32_e32 v83, v82, v80
	v_mul_f32_e32 v72, 0xbfb8aa3b, v87
	v_cvt_pk_bf16_f32 v80, v96, v95
	v_cvt_pk_bf16_f32 v81, v92, v90
	v_cvt_pk_bf16_f32 v82, v88, v89
	v_exp_f32_e32 v88, v72
	v_mov_b32_e32 v76, v73
	v_pk_mul_f32 v[72:73], v[76:77], v[170:171] op_sel_hi:[1,0]
	v_cvt_pk_bf16_f32 v83, v84, v83
	v_mad_i64_i32 v[84:85], s[4:5], v156, s51, v[112:113]
	v_mul_f32_e32 v76, 0xbfb8aa3b, v73
	v_exp_f32_e32 v89, v76
	v_lshl_add_u64 v[76:77], v[84:85], 0, v[114:115]
	v_add_f32_e32 v84, 1.0, v88
	v_rcp_f32_e32 v84, v84
	global_store_dwordx4 v[76:77], v[80:83], off
	v_mov_b32_e32 v77, v78
	v_add_f32_e32 v85, 1.0, v89
	v_mul_f32_e32 v76, v87, v84
	v_mul_f32_e32 v80, v86, v76
	v_mov_b32_e32 v76, v74
	v_pk_mul_f32 v[76:77], v[76:77], v[170:171] op_sel_hi:[1,0]
	v_mov_b32_e32 v78, v75
	v_mul_f32_e32 v74, 0xbfb8aa3b, v77
	v_rcp_f32_e32 v85, v85
	v_exp_f32_e32 v81, v74
	v_pk_mul_f32 v[74:75], v[78:79], v[170:171] op_sel_hi:[1,0]
	v_mul_f32_e32 v73, v73, v85
	v_mul_f32_e32 v78, 0xbfb8aa3b, v75
	v_exp_f32_e32 v78, v78
	v_mul_f32_e32 v79, v72, v73
	v_add_f32_e32 v72, 1.0, v81
	v_rcp_f32_e32 v81, v72
	v_add_f32_e32 v72, 1.0, v78
	v_rcp_f32_e32 v78, v72
	v_mov_b32_e32 v72, v64
	v_mov_b32_e32 v73, v68
	v_pk_mul_f32 v[72:73], v[72:73], v[170:171] op_sel_hi:[1,0]
	v_mul_f32_e32 v68, v77, v81
	v_mul_f32_e32 v64, 0xbfb8aa3b, v73
	v_exp_f32_e32 v64, v64
	v_mul_f32_e32 v76, v76, v68
	v_mov_b32_e32 v68, v65
	v_mul_f32_e32 v75, v75, v78
	v_add_f32_e32 v64, 1.0, v64
	v_rcp_f32_e32 v77, v64
	v_pk_mul_f32 v[64:65], v[68:69], v[170:171] op_sel_hi:[1,0]
	v_mul_f32_e32 v74, v74, v75
	v_mul_f32_e32 v68, 0xbfb8aa3b, v65
	v_exp_f32_e32 v68, v68
	v_mul_f32_e32 v69, v73, v77
	v_mul_f32_e32 v72, v72, v69
	v_mov_b32_e32 v69, v70
	v_add_f32_e32 v68, 1.0, v68
	v_rcp_f32_e32 v73, v68
	v_mov_b32_e32 v68, v66
	v_pk_mul_f32 v[68:69], v[68:69], v[170:171] op_sel_hi:[1,0]
	v_mov_b32_e32 v70, v67
	v_mul_f32_e32 v66, 0xbfb8aa3b, v69
	v_exp_f32_e32 v75, v66
	v_pk_mul_f32 v[66:67], v[70:71], v[170:171] op_sel_hi:[1,0]
	v_mul_f32_e32 v65, v65, v73
	v_mul_f32_e32 v70, 0xbfb8aa3b, v67
	v_exp_f32_e32 v70, v70
	v_add_f32_e32 v71, 1.0, v75
	v_rcp_f32_e32 v71, v71
	v_mul_f32_e32 v73, v64, v65
	v_add_f32_e32 v70, 1.0, v70
	v_rcp_f32_e32 v70, v70
	v_mul_f32_e32 v64, v69, v71
	v_mul_f32_e32 v68, v68, v64
	v_mov_b32_e32 v71, v60
	v_mul_f32_e32 v64, v67, v70
	v_mov_b32_e32 v70, v56
	v_pk_mul_f32 v[70:71], v[70:71], v[168:169] op_sel_hi:[1,0]
	v_mul_f32_e32 v67, v66, v64
	v_mul_f32_e32 v56, 0xbfb8aa3b, v71
	v_cvt_pk_bf16_f32 v64, v80, v79
	v_cvt_pk_bf16_f32 v65, v76, v74
	v_cvt_pk_bf16_f32 v66, v72, v73
	v_exp_f32_e32 v72, v56
	v_mov_b32_e32 v60, v57
	v_pk_mul_f32 v[56:57], v[60:61], v[168:169] op_sel_hi:[1,0]
	v_cvt_pk_bf16_f32 v67, v68, v67
	v_mad_i64_i32 v[68:69], s[4:5], v154, s51, v[112:113]
	v_mul_f32_e32 v60, 0xbfb8aa3b, v57
	v_exp_f32_e32 v73, v60
	v_lshl_add_u64 v[60:61], v[68:69], 0, v[114:115]
	v_add_f32_e32 v68, 1.0, v72
	v_rcp_f32_e32 v68, v68
	global_store_dwordx4 v[60:61], v[64:67], off
	v_mov_b32_e32 v61, v62
	v_add_f32_e32 v69, 1.0, v73
	v_mul_f32_e32 v60, v71, v68
	v_mul_f32_e32 v64, v70, v60
	v_mov_b32_e32 v60, v58
	v_pk_mul_f32 v[60:61], v[60:61], v[168:169] op_sel_hi:[1,0]
	v_mov_b32_e32 v62, v59
	v_mul_f32_e32 v58, 0xbfb8aa3b, v61
	v_rcp_f32_e32 v69, v69
	v_exp_f32_e32 v65, v58
	v_pk_mul_f32 v[58:59], v[62:63], v[168:169] op_sel_hi:[1,0]
	v_mul_f32_e32 v57, v57, v69
	v_mul_f32_e32 v62, 0xbfb8aa3b, v59
	v_exp_f32_e32 v62, v62
	v_mul_f32_e32 v63, v56, v57
	v_add_f32_e32 v56, 1.0, v65
	v_rcp_f32_e32 v65, v56
	v_add_f32_e32 v56, 1.0, v62
	v_rcp_f32_e32 v62, v56
	v_mov_b32_e32 v56, v48
	v_mov_b32_e32 v57, v52
	v_pk_mul_f32 v[56:57], v[56:57], v[168:169] op_sel_hi:[1,0]
	v_mul_f32_e32 v52, v61, v65
	v_mul_f32_e32 v48, 0xbfb8aa3b, v57
	v_exp_f32_e32 v48, v48
	v_mul_f32_e32 v60, v60, v52
	v_mov_b32_e32 v52, v49
	v_mul_f32_e32 v59, v59, v62
	v_add_f32_e32 v48, 1.0, v48
	v_rcp_f32_e32 v61, v48
	v_pk_mul_f32 v[48:49], v[52:53], v[168:169] op_sel_hi:[1,0]
	v_mul_f32_e32 v58, v58, v59
	v_mul_f32_e32 v52, 0xbfb8aa3b, v49
	v_exp_f32_e32 v52, v52
	v_mul_f32_e32 v53, v57, v61
	v_mul_f32_e32 v56, v56, v53
	v_mov_b32_e32 v53, v54
	v_add_f32_e32 v52, 1.0, v52
	v_rcp_f32_e32 v57, v52
	v_mov_b32_e32 v52, v50
	v_pk_mul_f32 v[52:53], v[52:53], v[168:169] op_sel_hi:[1,0]
	v_mov_b32_e32 v54, v51
	v_mul_f32_e32 v50, 0xbfb8aa3b, v53
	v_exp_f32_e32 v59, v50
	v_pk_mul_f32 v[50:51], v[54:55], v[168:169] op_sel_hi:[1,0]
	v_mul_f32_e32 v49, v49, v57
	v_mul_f32_e32 v54, 0xbfb8aa3b, v51
	v_exp_f32_e32 v54, v54
	v_add_f32_e32 v55, 1.0, v59
	v_rcp_f32_e32 v55, v55
	v_mul_f32_e32 v57, v48, v49
	v_add_f32_e32 v54, 1.0, v54
	v_rcp_f32_e32 v54, v54
	v_mul_f32_e32 v48, v53, v55
	v_mul_f32_e32 v52, v52, v48
	v_mov_b32_e32 v55, v44
	v_mul_f32_e32 v48, v51, v54
	v_mov_b32_e32 v54, v40
	v_pk_mul_f32 v[54:55], v[54:55], v[166:167] op_sel_hi:[1,0]
	v_mul_f32_e32 v51, v50, v48
	v_mul_f32_e32 v40, 0xbfb8aa3b, v55
	v_cvt_pk_bf16_f32 v48, v64, v63
	v_cvt_pk_bf16_f32 v49, v60, v58
	v_cvt_pk_bf16_f32 v50, v56, v57
	v_exp_f32_e32 v56, v40
	v_mov_b32_e32 v44, v41
	v_pk_mul_f32 v[40:41], v[44:45], v[166:167] op_sel_hi:[1,0]
	v_cvt_pk_bf16_f32 v51, v52, v51
	v_mad_i64_i32 v[52:53], s[4:5], v148, s51, v[112:113]
	v_mul_f32_e32 v44, 0xbfb8aa3b, v41
	v_exp_f32_e32 v57, v44
	v_lshl_add_u64 v[44:45], v[52:53], 0, v[114:115]
	v_add_f32_e32 v52, 1.0, v56
	v_rcp_f32_e32 v52, v52
	global_store_dwordx4 v[44:45], v[48:51], off
	v_mov_b32_e32 v45, v46
	v_add_f32_e32 v53, 1.0, v57
	v_mul_f32_e32 v44, v55, v52
	v_mul_f32_e32 v48, v54, v44
	v_mov_b32_e32 v44, v42
	v_pk_mul_f32 v[44:45], v[44:45], v[166:167] op_sel_hi:[1,0]
	v_mov_b32_e32 v46, v43
	v_mul_f32_e32 v42, 0xbfb8aa3b, v45
	v_rcp_f32_e32 v53, v53
	v_exp_f32_e32 v49, v42
	v_pk_mul_f32 v[42:43], v[46:47], v[166:167] op_sel_hi:[1,0]
	v_mul_f32_e32 v41, v41, v53
	v_mul_f32_e32 v46, 0xbfb8aa3b, v43
	v_exp_f32_e32 v46, v46
	v_mul_f32_e32 v47, v40, v41
	v_add_f32_e32 v40, 1.0, v49
	v_rcp_f32_e32 v49, v40
	v_add_f32_e32 v40, 1.0, v46
	v_rcp_f32_e32 v46, v40
	v_mov_b32_e32 v40, v32
	v_mov_b32_e32 v41, v36
	v_pk_mul_f32 v[40:41], v[40:41], v[166:167] op_sel_hi:[1,0]
	v_mul_f32_e32 v36, v45, v49
	v_mul_f32_e32 v32, 0xbfb8aa3b, v41
	v_exp_f32_e32 v32, v32
	v_mul_f32_e32 v44, v44, v36
	v_mov_b32_e32 v36, v33
	v_mul_f32_e32 v43, v43, v46
	v_add_f32_e32 v32, 1.0, v32
	v_rcp_f32_e32 v45, v32
	v_pk_mul_f32 v[32:33], v[36:37], v[166:167] op_sel_hi:[1,0]
	v_mul_f32_e32 v42, v42, v43
	v_mul_f32_e32 v36, 0xbfb8aa3b, v33
	v_exp_f32_e32 v36, v36
	v_mul_f32_e32 v37, v41, v45
	v_mul_f32_e32 v40, v40, v37
	v_mov_b32_e32 v37, v38
	v_add_f32_e32 v36, 1.0, v36
	v_rcp_f32_e32 v41, v36
	v_mov_b32_e32 v36, v34
	v_pk_mul_f32 v[36:37], v[36:37], v[166:167] op_sel_hi:[1,0]
	v_mov_b32_e32 v38, v35
	v_mul_f32_e32 v34, 0xbfb8aa3b, v37
	v_exp_f32_e32 v43, v34
	v_pk_mul_f32 v[34:35], v[38:39], v[166:167] op_sel_hi:[1,0]
	v_mul_f32_e32 v33, v33, v41
	v_mul_f32_e32 v38, 0xbfb8aa3b, v35
	v_exp_f32_e32 v38, v38
	v_add_f32_e32 v39, 1.0, v43
	v_rcp_f32_e32 v39, v39
	v_mul_f32_e32 v41, v32, v33
	v_add_f32_e32 v38, 1.0, v38
	v_rcp_f32_e32 v38, v38
	v_mul_f32_e32 v32, v37, v39
	v_mul_f32_e32 v36, v36, v32
	v_mov_b32_e32 v39, v28
	v_mul_f32_e32 v32, v35, v38
	v_mov_b32_e32 v38, v24
	v_pk_mul_f32 v[38:39], v[38:39], v[164:165] op_sel_hi:[1,0]
	v_mul_f32_e32 v35, v34, v32
	v_mul_f32_e32 v24, 0xbfb8aa3b, v39
	v_cvt_pk_bf16_f32 v32, v48, v47
	v_cvt_pk_bf16_f32 v33, v44, v42
	v_cvt_pk_bf16_f32 v34, v40, v41
	v_exp_f32_e32 v40, v24
	v_mov_b32_e32 v28, v25
	v_pk_mul_f32 v[24:25], v[28:29], v[164:165] op_sel_hi:[1,0]
	v_cvt_pk_bf16_f32 v35, v36, v35
	v_mad_i64_i32 v[36:37], s[4:5], v152, s51, v[112:113]
	v_mul_f32_e32 v28, 0xbfb8aa3b, v25
	v_exp_f32_e32 v41, v28
	v_lshl_add_u64 v[28:29], v[36:37], 0, v[114:115]
	v_add_f32_e32 v36, 1.0, v40
	v_rcp_f32_e32 v36, v36
	global_store_dwordx4 v[28:29], v[32:35], off
	v_mov_b32_e32 v29, v30
	v_add_f32_e32 v37, 1.0, v41
	v_mul_f32_e32 v28, v39, v36
	v_mul_f32_e32 v32, v38, v28
	v_mov_b32_e32 v28, v26
	v_pk_mul_f32 v[28:29], v[28:29], v[164:165] op_sel_hi:[1,0]
	v_mov_b32_e32 v30, v27
	v_mul_f32_e32 v26, 0xbfb8aa3b, v29
	v_rcp_f32_e32 v37, v37
	v_exp_f32_e32 v33, v26
	v_pk_mul_f32 v[26:27], v[30:31], v[164:165] op_sel_hi:[1,0]
	v_mul_f32_e32 v25, v25, v37
	v_mul_f32_e32 v30, 0xbfb8aa3b, v27
	v_exp_f32_e32 v30, v30
	v_mul_f32_e32 v31, v24, v25
	v_add_f32_e32 v24, 1.0, v33
	v_rcp_f32_e32 v33, v24
	v_add_f32_e32 v24, 1.0, v30
	v_rcp_f32_e32 v30, v24
	v_mov_b32_e32 v24, v16
	v_mov_b32_e32 v25, v20
	v_pk_mul_f32 v[24:25], v[24:25], v[164:165] op_sel_hi:[1,0]
	v_mul_f32_e32 v20, v29, v33
	v_mul_f32_e32 v16, 0xbfb8aa3b, v25
	v_exp_f32_e32 v16, v16
	v_mul_f32_e32 v28, v28, v20
	v_mov_b32_e32 v20, v17
	v_mul_f32_e32 v27, v27, v30
	v_add_f32_e32 v16, 1.0, v16
	v_rcp_f32_e32 v29, v16
	v_pk_mul_f32 v[16:17], v[20:21], v[164:165] op_sel_hi:[1,0]
	v_mul_f32_e32 v26, v26, v27
	v_mul_f32_e32 v20, 0xbfb8aa3b, v17
	v_exp_f32_e32 v20, v20
	v_mul_f32_e32 v21, v25, v29
	v_mul_f32_e32 v24, v24, v21
	v_mov_b32_e32 v21, v22
	v_add_f32_e32 v20, 1.0, v20
	v_rcp_f32_e32 v25, v20
	v_mov_b32_e32 v20, v18
	v_pk_mul_f32 v[20:21], v[20:21], v[164:165] op_sel_hi:[1,0]
	v_mov_b32_e32 v22, v19
	v_mul_f32_e32 v18, 0xbfb8aa3b, v21
	v_exp_f32_e32 v27, v18
	v_pk_mul_f32 v[18:19], v[22:23], v[164:165] op_sel_hi:[1,0]
	v_mul_f32_e32 v17, v17, v25
	v_mul_f32_e32 v22, 0xbfb8aa3b, v19
	v_exp_f32_e32 v22, v22
	v_add_f32_e32 v23, 1.0, v27
	v_rcp_f32_e32 v23, v23
	v_mul_f32_e32 v25, v16, v17
	v_add_f32_e32 v22, 1.0, v22
	v_rcp_f32_e32 v22, v22
	v_mul_f32_e32 v16, v21, v23
	v_mul_f32_e32 v20, v20, v16
	v_mov_b32_e32 v23, v12
	v_mul_f32_e32 v16, v19, v22
	v_mov_b32_e32 v22, v8
	v_pk_mul_f32 v[22:23], v[22:23], v[158:159] op_sel_hi:[1,0]
	v_mul_f32_e32 v19, v18, v16
	v_mul_f32_e32 v8, 0xbfb8aa3b, v23
	v_cvt_pk_bf16_f32 v16, v32, v31
	v_cvt_pk_bf16_f32 v17, v28, v26
	v_cvt_pk_bf16_f32 v18, v24, v25
	v_exp_f32_e32 v24, v8
	v_mov_b32_e32 v12, v9
	v_pk_mul_f32 v[8:9], v[12:13], v[158:159] op_sel_hi:[1,0]
	v_cvt_pk_bf16_f32 v19, v20, v19
	v_mad_i64_i32 v[20:21], s[4:5], v150, s51, v[112:113]
	v_mul_f32_e32 v12, 0xbfb8aa3b, v9
	v_exp_f32_e32 v25, v12
	v_lshl_add_u64 v[12:13], v[20:21], 0, v[114:115]
	v_add_f32_e32 v20, 1.0, v24
	v_rcp_f32_e32 v20, v20
	global_store_dwordx4 v[12:13], v[16:19], off
	v_mov_b32_e32 v13, v14
	v_add_f32_e32 v21, 1.0, v25
	v_mul_f32_e32 v12, v23, v20
	v_mul_f32_e32 v16, v22, v12
	v_mov_b32_e32 v12, v10
	v_pk_mul_f32 v[12:13], v[12:13], v[158:159] op_sel_hi:[1,0]
	v_mov_b32_e32 v14, v11
	v_mul_f32_e32 v10, 0xbfb8aa3b, v13
	v_rcp_f32_e32 v21, v21
	v_exp_f32_e32 v17, v10
	v_pk_mul_f32 v[10:11], v[14:15], v[158:159] op_sel_hi:[1,0]
	v_mul_f32_e32 v9, v9, v21
	v_mul_f32_e32 v14, 0xbfb8aa3b, v11
	v_exp_f32_e32 v14, v14
	v_mul_f32_e32 v15, v8, v9
	v_add_f32_e32 v8, 1.0, v17
	v_rcp_f32_e32 v17, v8
	v_add_f32_e32 v8, 1.0, v14
	v_rcp_f32_e32 v14, v8
	v_mov_b32_e32 v8, v0
	v_mov_b32_e32 v9, v4
	v_pk_mul_f32 v[8:9], v[8:9], v[158:159] op_sel_hi:[1,0]
	v_mul_f32_e32 v4, v13, v17
	v_mul_f32_e32 v0, 0xbfb8aa3b, v9
	v_exp_f32_e32 v0, v0
	v_mul_f32_e32 v12, v12, v4
	v_mov_b32_e32 v4, v1
	v_mul_f32_e32 v11, v11, v14
	v_add_f32_e32 v0, 1.0, v0
	v_rcp_f32_e32 v13, v0
	v_pk_mul_f32 v[0:1], v[4:5], v[158:159] op_sel_hi:[1,0]
	v_mul_f32_e32 v10, v10, v11
	v_mul_f32_e32 v4, 0xbfb8aa3b, v1
	v_exp_f32_e32 v4, v4
	v_mul_f32_e32 v5, v9, v13
	v_mul_f32_e32 v8, v8, v5
	v_mov_b32_e32 v5, v6
	v_add_f32_e32 v4, 1.0, v4
	v_rcp_f32_e32 v9, v4
	v_mov_b32_e32 v4, v2
	v_pk_mul_f32 v[4:5], v[4:5], v[158:159] op_sel_hi:[1,0]
	v_mov_b32_e32 v6, v3
	v_mul_f32_e32 v2, 0xbfb8aa3b, v5
	v_exp_f32_e32 v11, v2
	v_pk_mul_f32 v[2:3], v[6:7], v[158:159] op_sel_hi:[1,0]
	v_mul_f32_e32 v1, v1, v9
	v_mul_f32_e32 v6, 0xbfb8aa3b, v3
	v_exp_f32_e32 v6, v6
	v_add_f32_e32 v7, 1.0, v11
	v_rcp_f32_e32 v7, v7
	v_mul_f32_e32 v9, v0, v1
	v_add_f32_e32 v6, 1.0, v6
	v_rcp_f32_e32 v6, v6
	v_mul_f32_e32 v0, v5, v7
	v_mul_f32_e32 v4, v4, v0
	v_mul_f32_e32 v0, v3, v6
	v_mul_f32_e32 v3, v2, v0
	v_cvt_pk_bf16_f32 v0, v16, v15
	v_cvt_pk_bf16_f32 v1, v12, v10
	v_cvt_pk_bf16_f32 v2, v8, v9
	v_cvt_pk_bf16_f32 v3, v4, v3
	v_mad_i64_i32 v[4:5], s[4:5], v146, s51, v[112:113]
	v_lshl_add_u64 v[4:5], v[4:5], 0, v[114:115]
	s_mov_b64 s[4:5], -1
	global_store_dwordx4 v[4:5], v[0:3], off
	s_cbranch_vccnz .LBB0_1044
	s_andn2_b64 vcc, exec, s[16:17]
	s_cbranch_vccnz .LBB0_1043
	s_barrier
	s_branch .LBB0_1043
